# removed the 32 redundant s_waitcnt lgkmcnt(0) that follow s_barrier + s_setprio 1 ahead of each GEMM MFMA block (v087 otherwise)
# baseline (speedup 1.0000x reference)
.LBB0_538:
	ds_read_b128 v[152:155], v149
	ds_read_b128 v[156:159], v149 offset:1024
	ds_read_b128 v[160:163], v149 offset:2048
	ds_read_b128 v[164:167], v149 offset:3072
	ds_read_b128 v[168:171], v150
	ds_read_b128 v[172:175], v150 offset:1024
	ds_read_b128 v[176:179], v150 offset:2048
	ds_read_b128 v[180:183], v150 offset:3072
	s_add_u32 s40, s38, 0xfffc0080
	s_addc_u32 s41, s39, -1
	s_cmp_eq_u32 s54, 12
	s_cselect_b32 s43, s27, s41
	s_cselect_b32 s42, s50, s40
	s_cselect_b32 s41, s25, s53
	s_cselect_b32 s40, s51, s52
	s_add_i32 m0, s11, 0xc000
	ds_read_b128 v[184:187], v151
	ds_read_b128 v[188:191], v151 offset:1024
	ds_read_b128 v[192:195], v151 offset:2048
	ds_read_b128 v[196:199], v151 offset:3072
	ds_read_b128 v[200:203], v151 offset:4096
	ds_read_b128 v[204:207], v151 offset:5120
	ds_read_b128 v[212:215], v151 offset:6144
	ds_read_b128 v[216:219], v151 offset:7168
	global_load_lds_dwordx4 v136, s[38:39]
	s_add_i32 m0, s11, 0xe000
	s_nop 0
	global_load_lds_dwordx4 v138, s[38:39]
	s_waitcnt vmcnt(8)
	s_waitcnt lgkmcnt(0)
	s_barrier
	s_setprio 1
	v_mfma_f32_16x16x32_bf16 v[124:127], v[152:155], v[184:187], v[124:127]
	v_mfma_f32_16x16x32_bf16 v[120:123], v[160:163], v[184:187], v[120:123]
	v_mfma_f32_16x16x32_bf16 v[108:111], v[152:155], v[192:195], v[108:111]
	v_mfma_f32_16x16x32_bf16 v[104:107], v[160:163], v[192:195], v[104:107]
	v_mfma_f32_16x16x32_bf16 v[92:95], v[152:155], v[200:203], v[92:95]
	v_mfma_f32_16x16x32_bf16 v[88:91], v[160:163], v[200:203], v[88:91]
	v_mfma_f32_16x16x32_bf16 v[76:79], v[152:155], v[212:215], v[76:79]
	v_mfma_f32_16x16x32_bf16 v[72:75], v[160:163], v[212:215], v[72:75]
	v_mfma_f32_16x16x32_bf16 v[124:127], v[156:159], v[188:191], v[124:127]
	v_mfma_f32_16x16x32_bf16 v[120:123], v[164:167], v[188:191], v[120:123]
	v_mfma_f32_16x16x32_bf16 v[108:111], v[156:159], v[196:199], v[108:111]
	v_mfma_f32_16x16x32_bf16 v[104:107], v[164:167], v[196:199], v[104:107]
	v_mfma_f32_16x16x32_bf16 v[92:95], v[156:159], v[204:207], v[92:95]
	v_mfma_f32_16x16x32_bf16 v[88:91], v[164:167], v[204:207], v[88:91]
	v_mfma_f32_16x16x32_bf16 v[76:79], v[156:159], v[216:219], v[76:79]
	v_mfma_f32_16x16x32_bf16 v[72:75], v[164:167], v[216:219], v[72:75]
	s_setprio 0
	s_setprio 1
	v_mfma_f32_16x16x32_bf16 v[116:119], v[168:171], v[184:187], v[116:119]
	v_mfma_f32_16x16x32_bf16 v[112:115], v[176:179], v[184:187], v[112:115]
	v_mfma_f32_16x16x32_bf16 v[100:103], v[168:171], v[192:195], v[100:103]
	v_mfma_f32_16x16x32_bf16 v[96:99], v[176:179], v[192:195], v[96:99]
	v_mfma_f32_16x16x32_bf16 v[84:87], v[168:171], v[200:203], v[84:87]
	v_mfma_f32_16x16x32_bf16 v[80:83], v[176:179], v[200:203], v[80:83]
	v_mfma_f32_16x16x32_bf16 v[68:71], v[168:171], v[212:215], v[68:71]
	v_mfma_f32_16x16x32_bf16 v[64:67], v[176:179], v[212:215], v[64:67]
	v_mfma_f32_16x16x32_bf16 v[116:119], v[172:175], v[188:191], v[116:119]
	v_mfma_f32_16x16x32_bf16 v[112:115], v[180:183], v[188:191], v[112:115]
	v_mfma_f32_16x16x32_bf16 v[100:103], v[172:175], v[196:199], v[100:103]
	v_mfma_f32_16x16x32_bf16 v[96:99], v[180:183], v[196:199], v[96:99]
	v_mfma_f32_16x16x32_bf16 v[84:87], v[172:175], v[204:207], v[84:87]
	v_mfma_f32_16x16x32_bf16 v[80:83], v[180:183], v[204:207], v[80:83]
	v_mfma_f32_16x16x32_bf16 v[68:71], v[172:175], v[216:219], v[68:71]
	v_mfma_f32_16x16x32_bf16 v[64:67], v[180:183], v[216:219], v[64:67]
	s_setprio 0
	s_barrier
	s_add_i32 s55, s45, s10
	v_lshl_add_u64 v[144:145], s[40:41], 0, v[132:133]
	s_mov_b32 m0, s55
	ds_read_b128 v[184:187], v151 offset:16384
	ds_read_b128 v[188:191], v151 offset:17408
	ds_read_b128 v[192:195], v151 offset:18432
	ds_read_b128 v[196:199], v151 offset:19456
	ds_read_b128 v[200:203], v151 offset:20480
	ds_read_b128 v[204:207], v151 offset:21504
	ds_read_b128 v[212:215], v151 offset:22528
	ds_read_b128 v[216:219], v151 offset:23552
	global_load_lds_dwordx4 v[144:145], off
	s_add_i32 m0, s55, 0x2000
	s_add_u32 s56, s40, 0x40000
	v_lshl_add_u64 v[208:209], s[40:41], 0, v[128:129]
	s_addc_u32 s57, s41, 0
	s_add_i32 s55, s46, s10
	global_load_lds_dwordx4 v[208:209], off
	s_mov_b32 m0, s55
	v_lshl_add_u64 v[222:223], s[42:43], 0, v[130:131]
	global_load_lds_dwordx4 v132, s[56:57]
	s_add_i32 m0, s55, 0x2000
	s_nop 0
	global_load_lds_dwordx4 v128, s[56:57]
	v_lshl_add_u64 v[220:221], s[42:43], 0, v[134:135]
	s_mov_b32 m0, s11
	s_nop 0
	global_load_lds_dwordx4 v[220:221], off
	s_mov_b32 m0, s14
	s_nop 0
	global_load_lds_dwordx4 v[222:223], off
	s_waitcnt vmcnt(8)
	s_waitcnt lgkmcnt(0)
	s_barrier
	s_setprio 1
	v_mfma_f32_16x16x32_bf16 v[60:63], v[152:155], v[184:187], v[60:63]
	v_mfma_f32_16x16x32_bf16 v[56:59], v[160:163], v[184:187], v[56:59]
	v_mfma_f32_16x16x32_bf16 v[44:47], v[152:155], v[192:195], v[44:47]
	v_mfma_f32_16x16x32_bf16 v[40:43], v[160:163], v[192:195], v[40:43]
	v_mfma_f32_16x16x32_bf16 v[28:31], v[152:155], v[200:203], v[28:31]
	v_mfma_f32_16x16x32_bf16 v[24:27], v[160:163], v[200:203], v[24:27]
	v_mfma_f32_16x16x32_bf16 v[12:15], v[152:155], v[212:215], v[12:15]
	v_mfma_f32_16x16x32_bf16 v[8:11], v[160:163], v[212:215], v[8:11]
	v_mfma_f32_16x16x32_bf16 v[60:63], v[156:159], v[188:191], v[60:63]
	v_mfma_f32_16x16x32_bf16 v[56:59], v[164:167], v[188:191], v[56:59]
	v_mfma_f32_16x16x32_bf16 v[44:47], v[156:159], v[196:199], v[44:47]
	v_mfma_f32_16x16x32_bf16 v[40:43], v[164:167], v[196:199], v[40:43]
	v_mfma_f32_16x16x32_bf16 v[28:31], v[156:159], v[204:207], v[28:31]
	v_mfma_f32_16x16x32_bf16 v[24:27], v[164:167], v[204:207], v[24:27]
	v_mfma_f32_16x16x32_bf16 v[12:15], v[156:159], v[216:219], v[12:15]
	v_mfma_f32_16x16x32_bf16 v[8:11], v[164:167], v[216:219], v[8:11]
	s_setprio 0
	s_setprio 1
	v_mfma_f32_16x16x32_bf16 v[52:55], v[168:171], v[184:187], v[52:55]
	v_mfma_f32_16x16x32_bf16 v[48:51], v[176:179], v[184:187], v[48:51]
	v_mfma_f32_16x16x32_bf16 v[36:39], v[168:171], v[192:195], v[36:39]
	v_mfma_f32_16x16x32_bf16 v[32:35], v[176:179], v[192:195], v[32:35]
	v_mfma_f32_16x16x32_bf16 v[20:23], v[168:171], v[200:203], v[20:23]
	v_mfma_f32_16x16x32_bf16 v[16:19], v[176:179], v[200:203], v[16:19]
	v_mfma_f32_16x16x32_bf16 v[4:7], v[168:171], v[212:215], v[4:7]
	v_mfma_f32_16x16x32_bf16 v[0:3], v[176:179], v[212:215], v[0:3]
	v_mfma_f32_16x16x32_bf16 v[52:55], v[172:175], v[188:191], v[52:55]
	v_mfma_f32_16x16x32_bf16 v[48:51], v[180:183], v[188:191], v[48:51]
	v_mfma_f32_16x16x32_bf16 v[36:39], v[172:175], v[196:199], v[36:39]
	v_mfma_f32_16x16x32_bf16 v[32:35], v[180:183], v[196:199], v[32:35]
	v_mfma_f32_16x16x32_bf16 v[20:23], v[172:175], v[204:207], v[20:23]
	v_mfma_f32_16x16x32_bf16 v[16:19], v[180:183], v[204:207], v[16:19]
	v_mfma_f32_16x16x32_bf16 v[4:7], v[172:175], v[216:219], v[4:7]
	v_mfma_f32_16x16x32_bf16 v[0:3], v[180:183], v[216:219], v[0:3]
	s_setprio 0
	s_barrier
	s_add_i32 s55, 0, 0x18000
	s_add_i32 s56, 0, 0x1c000
	v_add_u32_e32 v164, s55, v147
	v_add_u32_e32 v180, s56, v147
	ds_read_b128 v[152:155], v164
	ds_read_b128 v[156:159], v164 offset:1024
	ds_read_b128 v[160:163], v164 offset:2048
	ds_read_b128 v[164:167], v164 offset:3072
	ds_read_b128 v[168:171], v180
	ds_read_b128 v[172:175], v180 offset:1024
	ds_read_b128 v[176:179], v180 offset:2048
	ds_read_b128 v[180:183], v180 offset:3072
	s_add_u32 s42, s42, 0x40000
	s_addc_u32 s43, s43, 0
	s_mov_b32 m0, s15
	ds_read_b128 v[184:187], v151 offset:32768
	ds_read_b128 v[188:191], v151 offset:33792
	ds_read_b128 v[192:195], v151 offset:34816
	ds_read_b128 v[196:199], v151 offset:35840
	ds_read_b128 v[200:203], v151 offset:36864
	ds_read_b128 v[204:207], v151 offset:37888
	ds_read_b128 v[212:215], v151 offset:38912
	ds_read_b128 v[216:219], v151 offset:39936
	global_load_lds_dwordx4 v134, s[42:43]
	s_mov_b32 m0, s28
	s_nop 0
	global_load_lds_dwordx4 v130, s[42:43]
	s_waitcnt vmcnt(8)
	s_waitcnt lgkmcnt(0)
	s_barrier
	s_setprio 1
	v_mfma_f32_16x16x32_bf16 v[124:127], v[152:155], v[184:187], v[124:127]
	v_mfma_f32_16x16x32_bf16 v[120:123], v[160:163], v[184:187], v[120:123]
	v_mfma_f32_16x16x32_bf16 v[108:111], v[152:155], v[192:195], v[108:111]
	v_mfma_f32_16x16x32_bf16 v[104:107], v[160:163], v[192:195], v[104:107]
	v_mfma_f32_16x16x32_bf16 v[92:95], v[152:155], v[200:203], v[92:95]
	v_mfma_f32_16x16x32_bf16 v[88:91], v[160:163], v[200:203], v[88:91]
	v_mfma_f32_16x16x32_bf16 v[76:79], v[152:155], v[212:215], v[76:79]
	v_mfma_f32_16x16x32_bf16 v[72:75], v[160:163], v[212:215], v[72:75]
	v_mfma_f32_16x16x32_bf16 v[124:127], v[156:159], v[188:191], v[124:127]
	v_mfma_f32_16x16x32_bf16 v[120:123], v[164:167], v[188:191], v[120:123]
	v_mfma_f32_16x16x32_bf16 v[108:111], v[156:159], v[196:199], v[108:111]
	v_mfma_f32_16x16x32_bf16 v[104:107], v[164:167], v[196:199], v[104:107]
	v_mfma_f32_16x16x32_bf16 v[92:95], v[156:159], v[204:207], v[92:95]
	v_mfma_f32_16x16x32_bf16 v[88:91], v[164:167], v[204:207], v[88:91]
	v_mfma_f32_16x16x32_bf16 v[76:79], v[156:159], v[216:219], v[76:79]
	v_mfma_f32_16x16x32_bf16 v[72:75], v[164:167], v[216:219], v[72:75]
	s_setprio 0
	s_setprio 1
	v_mfma_f32_16x16x32_bf16 v[116:119], v[168:171], v[184:187], v[116:119]
	v_mfma_f32_16x16x32_bf16 v[112:115], v[176:179], v[184:187], v[112:115]
	v_mfma_f32_16x16x32_bf16 v[100:103], v[168:171], v[192:195], v[100:103]
	v_mfma_f32_16x16x32_bf16 v[96:99], v[176:179], v[192:195], v[96:99]
	v_mfma_f32_16x16x32_bf16 v[84:87], v[168:171], v[200:203], v[84:87]
	v_mfma_f32_16x16x32_bf16 v[80:83], v[176:179], v[200:203], v[80:83]
	v_mfma_f32_16x16x32_bf16 v[68:71], v[168:171], v[212:215], v[68:71]
	v_mfma_f32_16x16x32_bf16 v[64:67], v[176:179], v[212:215], v[64:67]
	v_mfma_f32_16x16x32_bf16 v[116:119], v[172:175], v[188:191], v[116:119]
	v_mfma_f32_16x16x32_bf16 v[112:115], v[180:183], v[188:191], v[112:115]
	v_mfma_f32_16x16x32_bf16 v[100:103], v[172:175], v[196:199], v[100:103]
	v_mfma_f32_16x16x32_bf16 v[96:99], v[180:183], v[196:199], v[96:99]
	v_mfma_f32_16x16x32_bf16 v[84:87], v[172:175], v[204:207], v[84:87]
	v_mfma_f32_16x16x32_bf16 v[80:83], v[180:183], v[204:207], v[80:83]
	v_mfma_f32_16x16x32_bf16 v[68:71], v[172:175], v[216:219], v[68:71]
	v_mfma_f32_16x16x32_bf16 v[64:67], v[180:183], v[216:219], v[64:67]
	s_setprio 0
	s_barrier
	s_add_i32 s42, s55, s10
	v_lshl_add_u64 v[144:145], v[144:145], 0, s[4:5]
	s_mov_b32 m0, s42
	ds_read_b128 v[184:187], v151 offset:49152
	ds_read_b128 v[188:191], v151 offset:50176
	ds_read_b128 v[192:195], v151 offset:51200
	ds_read_b128 v[196:199], v151 offset:52224
	ds_read_b128 v[200:203], v151 offset:53248
	ds_read_b128 v[204:207], v151 offset:54272
	ds_read_b128 v[212:215], v151 offset:55296
	ds_read_b128 v[216:219], v151 offset:56320
	global_load_lds_dwordx4 v[144:145], off
	s_add_i32 m0, s42, 0x2000
	s_add_u32 s40, s40, 0x40080
	v_lshl_add_u64 v[144:145], v[208:209], 0, s[4:5]
	s_addc_u32 s41, s41, 0
	s_add_i32 s42, s56, s10
	global_load_lds_dwordx4 v[144:145], off
	s_mov_b32 m0, s42
	s_nop 0
	global_load_lds_dwordx4 v132, s[40:41]
	s_add_i32 m0, s42, 0x2000
	s_nop 0
	global_load_lds_dwordx4 v128, s[40:41]
	v_lshl_add_u64 v[144:145], v[220:221], 0, s[4:5]
	s_mov_b32 m0, s29
	s_nop 0
	global_load_lds_dwordx4 v[144:145], off
	v_lshl_add_u64 v[144:145], v[222:223], 0, s[4:5]
	s_mov_b32 m0, s33
	s_nop 0
	global_load_lds_dwordx4 v[144:145], off
	s_waitcnt vmcnt(8)
	s_waitcnt lgkmcnt(0)
	s_barrier
	s_setprio 1
	v_mfma_f32_16x16x32_bf16 v[60:63], v[152:155], v[184:187], v[60:63]
	v_mfma_f32_16x16x32_bf16 v[56:59], v[160:163], v[184:187], v[56:59]
	v_mfma_f32_16x16x32_bf16 v[44:47], v[152:155], v[192:195], v[44:47]
	v_mfma_f32_16x16x32_bf16 v[40:43], v[160:163], v[192:195], v[40:43]
	v_mfma_f32_16x16x32_bf16 v[28:31], v[152:155], v[200:203], v[28:31]
	v_mfma_f32_16x16x32_bf16 v[24:27], v[160:163], v[200:203], v[24:27]
	v_mfma_f32_16x16x32_bf16 v[12:15], v[152:155], v[212:215], v[12:15]
	v_mfma_f32_16x16x32_bf16 v[8:11], v[160:163], v[212:215], v[8:11]
	v_mfma_f32_16x16x32_bf16 v[60:63], v[156:159], v[188:191], v[60:63]
	v_mfma_f32_16x16x32_bf16 v[56:59], v[164:167], v[188:191], v[56:59]
	v_mfma_f32_16x16x32_bf16 v[44:47], v[156:159], v[196:199], v[44:47]
	v_mfma_f32_16x16x32_bf16 v[40:43], v[164:167], v[196:199], v[40:43]
	v_mfma_f32_16x16x32_bf16 v[28:31], v[156:159], v[204:207], v[28:31]
	v_mfma_f32_16x16x32_bf16 v[24:27], v[164:167], v[204:207], v[24:27]
	v_mfma_f32_16x16x32_bf16 v[12:15], v[156:159], v[216:219], v[12:15]
	v_mfma_f32_16x16x32_bf16 v[8:11], v[164:167], v[216:219], v[8:11]
	s_setprio 0
	s_setprio 1
	v_mfma_f32_16x16x32_bf16 v[52:55], v[168:171], v[184:187], v[52:55]
	v_mfma_f32_16x16x32_bf16 v[48:51], v[176:179], v[184:187], v[48:51]
	v_mfma_f32_16x16x32_bf16 v[36:39], v[168:171], v[192:195], v[36:39]
	v_mfma_f32_16x16x32_bf16 v[32:35], v[176:179], v[192:195], v[32:35]
	v_mfma_f32_16x16x32_bf16 v[20:23], v[168:171], v[200:203], v[20:23]
	v_mfma_f32_16x16x32_bf16 v[16:19], v[176:179], v[200:203], v[16:19]
	v_mfma_f32_16x16x32_bf16 v[4:7], v[168:171], v[212:215], v[4:7]
	v_mfma_f32_16x16x32_bf16 v[0:3], v[176:179], v[212:215], v[0:3]
	v_mfma_f32_16x16x32_bf16 v[52:55], v[172:175], v[188:191], v[52:55]
	v_mfma_f32_16x16x32_bf16 v[48:51], v[180:183], v[188:191], v[48:51]
	v_mfma_f32_16x16x32_bf16 v[36:39], v[172:175], v[196:199], v[36:39]
	v_mfma_f32_16x16x32_bf16 v[32:35], v[180:183], v[196:199], v[32:35]
	v_mfma_f32_16x16x32_bf16 v[20:23], v[172:175], v[204:207], v[20:23]
	v_mfma_f32_16x16x32_bf16 v[16:19], v[180:183], v[204:207], v[16:19]
	v_mfma_f32_16x16x32_bf16 v[4:7], v[172:175], v[216:219], v[4:7]
	v_mfma_f32_16x16x32_bf16 v[0:3], v[180:183], v[216:219], v[0:3]
	s_setprio 0
	s_barrier
	s_add_i32 s54, s54, 2
	s_add_u32 s38, s38, 0x100
	s_addc_u32 s39, s39, 0
	s_add_u32 s52, s52, 0x100
	s_addc_u32 s53, s53, 0
	s_cmp_gt_u32 s54, 13
	s_cbranch_scc0 .LBB0_538
	s_and_b64 vcc, exec, s[8:9]
	s_cbranch_vccz .LBB0_541
	s_barrier

.LBB0_617:
	ds_read_b128 v[32:35], v186
	ds_read_b128 v[36:39], v186 offset:1024
	ds_read_b128 v[40:43], v186 offset:2048
	ds_read_b128 v[44:47], v186 offset:3072
	ds_read_b128 v[48:51], v187
	ds_read_b128 v[52:55], v187 offset:1024
	ds_read_b128 v[56:59], v187 offset:2048
	ds_read_b128 v[60:63], v187 offset:3072
	s_add_u32 s38, s2, 0x100
	s_addc_u32 s39, s3, 0
	s_cmp_eq_u32 s52, 40
	s_cselect_b32 s43, s7, s39
	s_cselect_b32 s42, s6, s38
	s_cselect_b32 s41, s37, s51
	s_cselect_b32 s40, s36, s1
	s_add_i32 m0, s11, 0xc000
	ds_read_b128 v[176:179], v188
	ds_read_b128 v[190:193], v188 offset:1024
	ds_read_b128 v[194:197], v188 offset:2048
	ds_read_b128 v[198:201], v188 offset:3072
	ds_read_b128 v[202:205], v188 offset:4096
	ds_read_b128 v[206:209], v188 offset:5120
	ds_read_b128 v[212:215], v188 offset:6144
	ds_read_b128 v[216:219], v188 offset:7168
	global_load_lds_dwordx4 v168, s[2:3]
	s_add_i32 m0, s11, 0xe000
	s_nop 0
	global_load_lds_dwordx4 v170, s[2:3]
	s_waitcnt vmcnt(8)
	s_waitcnt lgkmcnt(0)
	s_barrier
	s_setprio 1
	v_mfma_f32_16x16x32_bf16 v[156:159], v[32:35], v[176:179], v[156:159]
	v_mfma_f32_16x16x32_bf16 v[152:155], v[40:43], v[176:179], v[152:155]
	v_mfma_f32_16x16x32_bf16 v[140:143], v[32:35], v[194:197], v[140:143]
	v_mfma_f32_16x16x32_bf16 v[136:139], v[40:43], v[194:197], v[136:139]
	v_mfma_f32_16x16x32_bf16 v[124:127], v[32:35], v[202:205], v[124:127]
	v_mfma_f32_16x16x32_bf16 v[120:123], v[40:43], v[202:205], v[120:123]
	v_mfma_f32_16x16x32_bf16 v[108:111], v[32:35], v[212:215], v[108:111]
	v_mfma_f32_16x16x32_bf16 v[104:107], v[40:43], v[212:215], v[104:107]
	v_mfma_f32_16x16x32_bf16 v[156:159], v[36:39], v[190:193], v[156:159]
	v_mfma_f32_16x16x32_bf16 v[152:155], v[44:47], v[190:193], v[152:155]
	v_mfma_f32_16x16x32_bf16 v[140:143], v[36:39], v[198:201], v[140:143]
	v_mfma_f32_16x16x32_bf16 v[136:139], v[44:47], v[198:201], v[136:139]
	v_mfma_f32_16x16x32_bf16 v[124:127], v[36:39], v[206:209], v[124:127]
	v_mfma_f32_16x16x32_bf16 v[120:123], v[44:47], v[206:209], v[120:123]
	v_mfma_f32_16x16x32_bf16 v[108:111], v[36:39], v[216:219], v[108:111]
	v_mfma_f32_16x16x32_bf16 v[104:107], v[44:47], v[216:219], v[104:107]
	s_setprio 0
	s_setprio 1
	v_mfma_f32_16x16x32_bf16 v[148:151], v[48:51], v[176:179], v[148:151]
	v_mfma_f32_16x16x32_bf16 v[144:147], v[56:59], v[176:179], v[144:147]
	v_mfma_f32_16x16x32_bf16 v[132:135], v[48:51], v[194:197], v[132:135]
	v_mfma_f32_16x16x32_bf16 v[128:131], v[56:59], v[194:197], v[128:131]
	v_mfma_f32_16x16x32_bf16 v[116:119], v[48:51], v[202:205], v[116:119]
	v_mfma_f32_16x16x32_bf16 v[112:115], v[56:59], v[202:205], v[112:115]
	v_mfma_f32_16x16x32_bf16 v[100:103], v[48:51], v[212:215], v[100:103]
	v_mfma_f32_16x16x32_bf16 v[96:99], v[56:59], v[212:215], v[96:99]
	v_mfma_f32_16x16x32_bf16 v[148:151], v[52:55], v[190:193], v[148:151]
	v_mfma_f32_16x16x32_bf16 v[144:147], v[60:63], v[190:193], v[144:147]
	v_mfma_f32_16x16x32_bf16 v[132:135], v[52:55], v[198:201], v[132:135]
	v_mfma_f32_16x16x32_bf16 v[128:131], v[60:63], v[198:201], v[128:131]
	v_mfma_f32_16x16x32_bf16 v[116:119], v[52:55], v[206:209], v[116:119]
	v_mfma_f32_16x16x32_bf16 v[112:115], v[60:63], v[206:209], v[112:115]
	v_mfma_f32_16x16x32_bf16 v[100:103], v[52:55], v[216:219], v[100:103]
	v_mfma_f32_16x16x32_bf16 v[96:99], v[60:63], v[216:219], v[96:99]
	s_setprio 0
	s_barrier
	s_add_i32 s2, s46, s10
	v_lshl_add_u64 v[180:181], s[40:41], 0, v[162:163]
	s_mov_b32 m0, s2
	ds_read_b128 v[176:179], v188 offset:16384
	ds_read_b128 v[190:193], v188 offset:17408
	ds_read_b128 v[194:197], v188 offset:18432
	ds_read_b128 v[198:201], v188 offset:19456
	ds_read_b128 v[202:205], v188 offset:20480
	ds_read_b128 v[206:209], v188 offset:21504
	ds_read_b128 v[212:215], v188 offset:22528
	ds_read_b128 v[216:219], v188 offset:23552
	global_load_lds_dwordx4 v[180:181], off
	s_add_i32 m0, s2, 0x2000
	s_add_u32 s2, s40, 0xb0000
	v_lshl_add_u64 v[228:229], s[40:41], 0, v[166:167]
	s_addc_u32 s3, s41, 0
	s_add_i32 s53, s47, s10
	global_load_lds_dwordx4 v[228:229], off
	s_mov_b32 m0, s53
	v_lshl_add_u64 v[230:231], s[42:43], 0, v[160:161]
	global_load_lds_dwordx4 v162, s[2:3]
	s_add_i32 m0, s53, 0x2000
	v_lshl_add_u64 v[232:233], s[42:43], 0, v[164:165]
	global_load_lds_dwordx4 v166, s[2:3]
	s_mov_b32 m0, s11
	s_nop 0
	global_load_lds_dwordx4 v[230:231], off
	s_mov_b32 m0, s14
	s_nop 0
	global_load_lds_dwordx4 v[232:233], off
	s_waitcnt vmcnt(8)
	s_waitcnt lgkmcnt(0)
	s_barrier
	s_setprio 1
	v_mfma_f32_16x16x32_bf16 v[92:95], v[32:35], v[176:179], v[92:95]
	v_mfma_f32_16x16x32_bf16 v[88:91], v[40:43], v[176:179], v[88:91]
	v_mfma_f32_16x16x32_bf16 v[76:79], v[32:35], v[194:197], v[76:79]
	v_mfma_f32_16x16x32_bf16 v[72:75], v[40:43], v[194:197], v[72:75]
	v_mfma_f32_16x16x32_bf16 v[28:31], v[32:35], v[202:205], v[28:31]
	v_mfma_f32_16x16x32_bf16 v[24:27], v[40:43], v[202:205], v[24:27]
	v_mfma_f32_16x16x32_bf16 v[12:15], v[32:35], v[212:215], v[12:15]
	v_mfma_f32_16x16x32_bf16 v[8:11], v[40:43], v[212:215], v[8:11]
	v_mfma_f32_16x16x32_bf16 v[92:95], v[36:39], v[190:193], v[92:95]
	v_mfma_f32_16x16x32_bf16 v[88:91], v[44:47], v[190:193], v[88:91]
	v_mfma_f32_16x16x32_bf16 v[76:79], v[36:39], v[198:201], v[76:79]
	v_mfma_f32_16x16x32_bf16 v[72:75], v[44:47], v[198:201], v[72:75]
	v_mfma_f32_16x16x32_bf16 v[28:31], v[36:39], v[206:209], v[28:31]
	v_mfma_f32_16x16x32_bf16 v[24:27], v[44:47], v[206:209], v[24:27]
	v_mfma_f32_16x16x32_bf16 v[12:15], v[36:39], v[216:219], v[12:15]
	v_mfma_f32_16x16x32_bf16 v[8:11], v[44:47], v[216:219], v[8:11]
	s_setprio 0
	s_setprio 1
	v_mfma_f32_16x16x32_bf16 v[20:23], v[48:51], v[202:205], v[20:23]
	v_mfma_f32_16x16x32_bf16 v[16:19], v[56:59], v[202:205], v[16:19]
	v_mfma_f32_16x16x32_bf16 v[4:7], v[48:51], v[212:215], v[4:7]
	v_mfma_f32_16x16x32_bf16 v[0:3], v[56:59], v[212:215], v[0:3]
	v_mfma_f32_16x16x32_bf16 v[32:35], v[48:51], v[176:179], v[84:87]
	v_mfma_f32_16x16x32_bf16 v[36:39], v[56:59], v[176:179], v[80:83]
	v_mfma_f32_16x16x32_bf16 v[40:43], v[48:51], v[194:197], v[68:71]
	v_mfma_f32_16x16x32_bf16 v[44:47], v[56:59], v[194:197], v[64:67]
	v_mfma_f32_16x16x32_bf16 v[20:23], v[52:55], v[206:209], v[20:23]
	v_mfma_f32_16x16x32_bf16 v[16:19], v[60:63], v[206:209], v[16:19]
	v_mfma_f32_16x16x32_bf16 v[4:7], v[52:55], v[216:219], v[4:7]
	v_mfma_f32_16x16x32_bf16 v[0:3], v[60:63], v[216:219], v[0:3]
	v_mfma_f32_16x16x32_bf16 v[32:35], v[52:55], v[190:193], v[32:35]
	v_mfma_f32_16x16x32_bf16 v[36:39], v[60:63], v[190:193], v[36:39]
	v_mfma_f32_16x16x32_bf16 v[40:43], v[52:55], v[198:201], v[40:43]
	v_mfma_f32_16x16x32_bf16 v[44:47], v[60:63], v[198:201], v[44:47]
	s_setprio 0
	s_barrier
	s_add_i32 s53, 0, 0x18000
	s_add_i32 s54, 0, 0x1c000
	v_add_u32_e32 v60, s53, v183
	v_add_u32_e32 v64, s54, v183
	ds_read_b128 v[48:51], v60
	ds_read_b128 v[52:55], v60 offset:1024
	ds_read_b128 v[56:59], v60 offset:2048
	ds_read_b128 v[60:63], v60 offset:3072
	ds_read_b128 v[176:179], v64
	ds_read_b128 v[190:193], v64 offset:1024
	ds_read_b128 v[194:197], v64 offset:2048
	ds_read_b128 v[198:201], v64 offset:3072
	s_add_u32 s2, s42, 0xb0000
	s_addc_u32 s3, s43, 0
	s_mov_b32 m0, s15
	ds_read_b128 v[64:67], v188 offset:32768
	ds_read_b128 v[68:71], v188 offset:33792
	ds_read_b128 v[80:83], v188 offset:34816
	ds_read_b128 v[84:87], v188 offset:35840
	ds_read_b128 v[202:205], v188 offset:36864
	ds_read_b128 v[206:209], v188 offset:37888
	ds_read_b128 v[212:215], v188 offset:38912
	ds_read_b128 v[216:219], v188 offset:39936
	global_load_lds_dwordx4 v160, s[2:3]
	s_mov_b32 m0, s28
	s_nop 0
	global_load_lds_dwordx4 v164, s[2:3]
	s_waitcnt vmcnt(8)
	s_waitcnt lgkmcnt(0)
	s_barrier
	s_setprio 1
	v_mfma_f32_16x16x32_bf16 v[156:159], v[48:51], v[64:67], v[156:159]
	v_mfma_f32_16x16x32_bf16 v[152:155], v[56:59], v[64:67], v[152:155]
	v_mfma_f32_16x16x32_bf16 v[140:143], v[48:51], v[80:83], v[140:143]
	v_mfma_f32_16x16x32_bf16 v[136:139], v[56:59], v[80:83], v[136:139]
	v_mfma_f32_16x16x32_bf16 v[124:127], v[48:51], v[202:205], v[124:127]
	v_mfma_f32_16x16x32_bf16 v[120:123], v[56:59], v[202:205], v[120:123]
	v_mfma_f32_16x16x32_bf16 v[108:111], v[48:51], v[212:215], v[108:111]
	v_mfma_f32_16x16x32_bf16 v[104:107], v[56:59], v[212:215], v[104:107]
	v_mfma_f32_16x16x32_bf16 v[156:159], v[52:55], v[68:71], v[156:159]
	v_mfma_f32_16x16x32_bf16 v[152:155], v[60:63], v[68:71], v[152:155]
	v_mfma_f32_16x16x32_bf16 v[140:143], v[52:55], v[84:87], v[140:143]
	v_mfma_f32_16x16x32_bf16 v[136:139], v[60:63], v[84:87], v[136:139]
	v_mfma_f32_16x16x32_bf16 v[124:127], v[52:55], v[206:209], v[124:127]
	v_mfma_f32_16x16x32_bf16 v[120:123], v[60:63], v[206:209], v[120:123]
	v_mfma_f32_16x16x32_bf16 v[108:111], v[52:55], v[216:219], v[108:111]
	v_mfma_f32_16x16x32_bf16 v[104:107], v[60:63], v[216:219], v[104:107]
	s_setprio 0
	s_setprio 1
	v_mfma_f32_16x16x32_bf16 v[148:151], v[176:179], v[64:67], v[148:151]
	v_mfma_f32_16x16x32_bf16 v[64:67], v[194:197], v[64:67], v[144:147]
	v_mfma_f32_16x16x32_bf16 v[144:147], v[198:201], v[68:71], v[64:67]
	v_mfma_f32_16x16x32_bf16 v[64:67], v[176:179], v[80:83], v[132:135]
	v_mfma_f32_16x16x32_bf16 v[132:135], v[190:193], v[84:87], v[64:67]
	v_mfma_f32_16x16x32_bf16 v[64:67], v[194:197], v[80:83], v[128:131]
	v_mfma_f32_16x16x32_bf16 v[128:131], v[198:201], v[84:87], v[64:67]
	v_mfma_f32_16x16x32_bf16 v[64:67], v[176:179], v[202:205], v[116:119]
	v_mfma_f32_16x16x32_bf16 v[116:119], v[190:193], v[206:209], v[64:67]
	v_mfma_f32_16x16x32_bf16 v[64:67], v[194:197], v[202:205], v[112:115]
	v_mfma_f32_16x16x32_bf16 v[112:115], v[198:201], v[206:209], v[64:67]
	v_mfma_f32_16x16x32_bf16 v[64:67], v[176:179], v[212:215], v[100:103]
	v_mfma_f32_16x16x32_bf16 v[100:103], v[190:193], v[216:219], v[64:67]
	v_mfma_f32_16x16x32_bf16 v[64:67], v[194:197], v[212:215], v[96:99]
	v_mfma_f32_16x16x32_bf16 v[148:151], v[190:193], v[68:71], v[148:151]
	v_mfma_f32_16x16x32_bf16 v[96:99], v[198:201], v[216:219], v[64:67]
	s_setprio 0
	s_barrier
	s_add_i32 s2, s53, s10
	v_lshl_add_u64 v[80:81], v[180:181], 0, s[26:27]
	s_mov_b32 m0, s2
	s_nop 0
	ds_read_b128 v[64:67], v188 offset:49152
	ds_read_b128 v[68:71], v188 offset:50176
	ds_read_b128 v[202:205], v188 offset:51200
	ds_read_b128 v[206:209], v188 offset:52224
	ds_read_b128 v[212:215], v188 offset:53248
	ds_read_b128 v[216:219], v188 offset:54272
	ds_read_b128 v[220:223], v188 offset:55296
	ds_read_b128 v[224:227], v188 offset:56320
	global_load_lds_dwordx4 v[80:81], off
	s_add_i32 m0, s2, 0x2000
	s_add_u32 s2, s40, 0xb0080
	v_lshl_add_u64 v[80:81], v[228:229], 0, s[26:27]
	s_addc_u32 s3, s41, 0
	s_add_i32 s40, s54, s10
	global_load_lds_dwordx4 v[80:81], off
	s_mov_b32 m0, s40
	s_nop 0
	global_load_lds_dwordx4 v162, s[2:3]
	s_add_i32 m0, s40, 0x2000
	s_nop 0
	global_load_lds_dwordx4 v166, s[2:3]
	v_lshl_add_u64 v[80:81], v[230:231], 0, s[26:27]
	s_mov_b32 m0, s33
	s_nop 0
	global_load_lds_dwordx4 v[80:81], off
	v_lshl_add_u64 v[80:81], v[232:233], 0, s[26:27]
	s_mov_b32 m0, s44
	s_nop 0
	global_load_lds_dwordx4 v[80:81], off
	s_waitcnt vmcnt(8)
	s_waitcnt lgkmcnt(0)
	s_barrier
	s_setprio 1
	v_mfma_f32_16x16x32_bf16 v[80:83], v[48:51], v[64:67], v[92:95]
	v_mfma_f32_16x16x32_bf16 v[92:95], v[52:55], v[68:71], v[80:83]
	v_mfma_f32_16x16x32_bf16 v[80:83], v[56:59], v[64:67], v[88:91]
	v_mfma_f32_16x16x32_bf16 v[76:79], v[48:51], v[202:205], v[76:79]
	v_mfma_f32_16x16x32_bf16 v[72:75], v[56:59], v[202:205], v[72:75]
	v_mfma_f32_16x16x32_bf16 v[28:31], v[48:51], v[212:215], v[28:31]
	v_mfma_f32_16x16x32_bf16 v[24:27], v[56:59], v[212:215], v[24:27]
	v_mfma_f32_16x16x32_bf16 v[12:15], v[48:51], v[220:223], v[12:15]
	v_mfma_f32_16x16x32_bf16 v[8:11], v[56:59], v[220:223], v[8:11]
	v_mfma_f32_16x16x32_bf16 v[88:91], v[60:63], v[68:71], v[80:83]
	v_mfma_f32_16x16x32_bf16 v[76:79], v[52:55], v[206:209], v[76:79]
	v_mfma_f32_16x16x32_bf16 v[72:75], v[60:63], v[206:209], v[72:75]
	v_mfma_f32_16x16x32_bf16 v[28:31], v[52:55], v[216:219], v[28:31]
	v_mfma_f32_16x16x32_bf16 v[24:27], v[60:63], v[216:219], v[24:27]
	v_mfma_f32_16x16x32_bf16 v[12:15], v[52:55], v[224:227], v[12:15]
	v_mfma_f32_16x16x32_bf16 v[8:11], v[60:63], v[224:227], v[8:11]
	s_setprio 0
	s_setprio 1
	v_mfma_f32_16x16x32_bf16 v[32:35], v[176:179], v[64:67], v[32:35]
	v_mfma_f32_16x16x32_bf16 v[84:87], v[190:193], v[68:71], v[32:35]
	v_mfma_f32_16x16x32_bf16 v[32:35], v[194:197], v[64:67], v[36:39]
	v_mfma_f32_16x16x32_bf16 v[80:83], v[198:201], v[68:71], v[32:35]
	v_mfma_f32_16x16x32_bf16 v[32:35], v[176:179], v[202:205], v[40:43]
	v_mfma_f32_16x16x32_bf16 v[68:71], v[190:193], v[206:209], v[32:35]
	v_mfma_f32_16x16x32_bf16 v[32:35], v[194:197], v[202:205], v[44:47]
	v_mfma_f32_16x16x32_bf16 v[20:23], v[176:179], v[212:215], v[20:23]
	v_mfma_f32_16x16x32_bf16 v[16:19], v[194:197], v[212:215], v[16:19]
	v_mfma_f32_16x16x32_bf16 v[4:7], v[176:179], v[220:223], v[4:7]
	v_mfma_f32_16x16x32_bf16 v[0:3], v[194:197], v[220:223], v[0:3]
	v_mfma_f32_16x16x32_bf16 v[64:67], v[198:201], v[206:209], v[32:35]
	v_mfma_f32_16x16x32_bf16 v[20:23], v[190:193], v[216:219], v[20:23]
	v_mfma_f32_16x16x32_bf16 v[16:19], v[198:201], v[216:219], v[16:19]
	v_mfma_f32_16x16x32_bf16 v[4:7], v[190:193], v[224:227], v[4:7]
	v_mfma_f32_16x16x32_bf16 v[0:3], v[198:201], v[224:227], v[0:3]
	s_setprio 0
	s_barrier
	s_add_i32 s52, s52, 2
	s_add_u32 s1, s1, 0x100
	s_addc_u32 s51, s51, 0
	s_cmp_gt_u32 s52, 41
	s_mov_b64 s[2:3], s[38:39]
	s_cbranch_scc0 .LBB0_617
	s_and_b64 vcc, exec, s[34:35]
	s_cbranch_vccz .LBB0_620
	s_barrier

.LBB0_704:
	ds_read_b128 v[128:131], v214
	ds_read_b128 v[132:135], v214 offset:1024
	ds_read_b128 v[136:139], v214 offset:2048
	ds_read_b128 v[140:143], v214 offset:3072
	ds_read_b128 v[144:147], v215
	ds_read_b128 v[148:151], v215 offset:1024
	ds_read_b128 v[168:171], v215 offset:2048
	ds_read_b128 v[172:175], v215 offset:3072
	s_add_u32 s6, s4, 0xfffc0080
	s_addc_u32 s7, s5, -1
	s_cmp_eq_u32 s57, 12
	s_cselect_b32 s63, s3, s7
	s_cselect_b32 s62, s11, s6
	s_cselect_b32 s7, s14, s55
	s_cselect_b32 s6, s15, s28
	s_add_i32 m0, s64, 0xc000
	ds_read_b128 v[176:179], v216
	ds_read_b128 v[180:183], v216 offset:1024
	ds_read_b128 v[184:187], v216 offset:2048
	ds_read_b128 v[188:191], v216 offset:3072
	ds_read_b128 v[192:195], v216 offset:4096
	ds_read_b128 v[196:199], v216 offset:5120
	ds_read_b128 v[200:203], v216 offset:6144
	ds_read_b128 v[204:207], v216 offset:7168
	global_load_lds_dwordx4 v160, s[4:5]
	s_add_i32 m0, s64, 0xe000
	s_nop 0
	global_load_lds_dwordx4 v162, s[4:5]
	s_waitcnt vmcnt(8)
	s_waitcnt lgkmcnt(0)
	s_barrier
	s_setprio 1
	v_mfma_f32_16x16x32_bf16 v[124:127], v[128:131], v[176:179], v[124:127]
	v_mfma_f32_16x16x32_bf16 v[120:123], v[136:139], v[176:179], v[120:123]
	v_mfma_f32_16x16x32_bf16 v[116:119], v[128:131], v[184:187], v[116:119]
	v_mfma_f32_16x16x32_bf16 v[112:115], v[136:139], v[184:187], v[112:115]
	v_mfma_f32_16x16x32_bf16 v[108:111], v[128:131], v[192:195], v[108:111]
	v_mfma_f32_16x16x32_bf16 v[100:103], v[136:139], v[192:195], v[100:103]
	v_mfma_f32_16x16x32_bf16 v[88:91], v[128:131], v[200:203], v[88:91]
	v_mfma_f32_16x16x32_bf16 v[80:83], v[136:139], v[200:203], v[80:83]
	v_mfma_f32_16x16x32_bf16 v[124:127], v[132:135], v[180:183], v[124:127]
	v_mfma_f32_16x16x32_bf16 v[120:123], v[140:143], v[180:183], v[120:123]
	v_mfma_f32_16x16x32_bf16 v[116:119], v[132:135], v[188:191], v[116:119]
	v_mfma_f32_16x16x32_bf16 v[112:115], v[140:143], v[188:191], v[112:115]
	v_mfma_f32_16x16x32_bf16 v[108:111], v[132:135], v[196:199], v[108:111]
	v_mfma_f32_16x16x32_bf16 v[100:103], v[140:143], v[196:199], v[100:103]
	v_mfma_f32_16x16x32_bf16 v[88:91], v[132:135], v[204:207], v[88:91]
	v_mfma_f32_16x16x32_bf16 v[80:83], v[140:143], v[204:207], v[80:83]
	s_setprio 0
	s_setprio 1
	v_mfma_f32_16x16x32_bf16 v[104:107], v[144:147], v[176:179], v[104:107]
	v_mfma_f32_16x16x32_bf16 v[96:99], v[168:171], v[176:179], v[96:99]
	v_mfma_f32_16x16x32_bf16 v[92:95], v[144:147], v[184:187], v[92:95]
	v_mfma_f32_16x16x32_bf16 v[84:87], v[168:171], v[184:187], v[84:87]
	v_mfma_f32_16x16x32_bf16 v[76:79], v[144:147], v[192:195], v[76:79]
	v_mfma_f32_16x16x32_bf16 v[72:75], v[168:171], v[192:195], v[72:75]
	v_mfma_f32_16x16x32_bf16 v[68:71], v[144:147], v[200:203], v[68:71]
	v_mfma_f32_16x16x32_bf16 v[64:67], v[168:171], v[200:203], v[64:67]
	v_mfma_f32_16x16x32_bf16 v[104:107], v[148:151], v[180:183], v[104:107]
	v_mfma_f32_16x16x32_bf16 v[96:99], v[172:175], v[180:183], v[96:99]
	v_mfma_f32_16x16x32_bf16 v[92:95], v[148:151], v[188:191], v[92:95]
	v_mfma_f32_16x16x32_bf16 v[84:87], v[172:175], v[188:191], v[84:87]
	v_mfma_f32_16x16x32_bf16 v[76:79], v[148:151], v[196:199], v[76:79]
	v_mfma_f32_16x16x32_bf16 v[72:75], v[172:175], v[196:199], v[72:75]
	v_mfma_f32_16x16x32_bf16 v[68:71], v[148:151], v[204:207], v[68:71]
	v_mfma_f32_16x16x32_bf16 v[64:67], v[172:175], v[204:207], v[64:67]
	s_setprio 0
	s_barrier
	s_add_i32 s68, s79, s33
	v_lshl_add_u64 v[208:209], s[6:7], 0, v[156:157]
	s_mov_b32 m0, s68
	ds_read_b128 v[176:179], v216 offset:16384
	ds_read_b128 v[180:183], v216 offset:17408
	ds_read_b128 v[184:187], v216 offset:18432
	ds_read_b128 v[188:191], v216 offset:19456
	ds_read_b128 v[192:195], v216 offset:20480
	ds_read_b128 v[196:199], v216 offset:21504
	ds_read_b128 v[200:203], v216 offset:22528
	ds_read_b128 v[204:207], v216 offset:23552
	global_load_lds_dwordx4 v[208:209], off
	s_add_i32 m0, s68, 0x2000
	s_add_u32 s84, s6, 0x40000
	v_lshl_add_u64 v[220:221], s[6:7], 0, v[152:153]
	s_addc_u32 s85, s7, 0
	s_add_i32 s68, s80, s33
	global_load_lds_dwordx4 v[220:221], off
	s_mov_b32 m0, s68
	v_lshl_add_u64 v[224:225], s[62:63], 0, v[154:155]
	global_load_lds_dwordx4 v156, s[84:85]
	s_add_i32 m0, s68, 0x2000
	s_nop 0
	global_load_lds_dwordx4 v152, s[84:85]
	v_lshl_add_u64 v[222:223], s[62:63], 0, v[158:159]
	s_mov_b32 m0, s64
	s_nop 0
	global_load_lds_dwordx4 v[222:223], off
	s_mov_b32 m0, s65
	s_nop 0
	global_load_lds_dwordx4 v[224:225], off
	s_waitcnt vmcnt(8)
	s_waitcnt lgkmcnt(0)
	s_barrier
	s_setprio 1
	v_mfma_f32_16x16x32_bf16 v[60:63], v[128:131], v[176:179], v[60:63]
	v_mfma_f32_16x16x32_bf16 v[56:59], v[136:139], v[176:179], v[56:59]
	v_mfma_f32_16x16x32_bf16 v[52:55], v[128:131], v[184:187], v[52:55]
	v_mfma_f32_16x16x32_bf16 v[48:51], v[136:139], v[184:187], v[48:51]
	v_mfma_f32_16x16x32_bf16 v[40:43], v[128:131], v[192:195], v[40:43]
	v_mfma_f32_16x16x32_bf16 v[32:35], v[136:139], v[192:195], v[32:35]
	v_mfma_f32_16x16x32_bf16 v[20:23], v[128:131], v[200:203], v[20:23]
	v_mfma_f32_16x16x32_bf16 v[16:19], v[136:139], v[200:203], v[16:19]
	v_mfma_f32_16x16x32_bf16 v[60:63], v[132:135], v[180:183], v[60:63]
	v_mfma_f32_16x16x32_bf16 v[56:59], v[140:143], v[180:183], v[56:59]
	v_mfma_f32_16x16x32_bf16 v[52:55], v[132:135], v[188:191], v[52:55]
	v_mfma_f32_16x16x32_bf16 v[48:51], v[140:143], v[188:191], v[48:51]
	v_mfma_f32_16x16x32_bf16 v[40:43], v[132:135], v[196:199], v[40:43]
	v_mfma_f32_16x16x32_bf16 v[32:35], v[140:143], v[196:199], v[32:35]
	v_mfma_f32_16x16x32_bf16 v[20:23], v[132:135], v[204:207], v[20:23]
	v_mfma_f32_16x16x32_bf16 v[16:19], v[140:143], v[204:207], v[16:19]
	s_setprio 0
	s_setprio 1
	v_mfma_f32_16x16x32_bf16 v[44:47], v[144:147], v[176:179], v[44:47]
	v_mfma_f32_16x16x32_bf16 v[36:39], v[168:171], v[176:179], v[36:39]
	v_mfma_f32_16x16x32_bf16 v[28:31], v[144:147], v[184:187], v[28:31]
	v_mfma_f32_16x16x32_bf16 v[24:27], v[168:171], v[184:187], v[24:27]
	v_mfma_f32_16x16x32_bf16 v[12:15], v[144:147], v[192:195], v[12:15]
	v_mfma_f32_16x16x32_bf16 v[8:11], v[168:171], v[192:195], v[8:11]
	v_mfma_f32_16x16x32_bf16 v[4:7], v[144:147], v[200:203], v[4:7]
	v_mfma_f32_16x16x32_bf16 v[0:3], v[168:171], v[200:203], v[0:3]
	v_mfma_f32_16x16x32_bf16 v[44:47], v[148:151], v[180:183], v[44:47]
	v_mfma_f32_16x16x32_bf16 v[36:39], v[172:175], v[180:183], v[36:39]
	v_mfma_f32_16x16x32_bf16 v[28:31], v[148:151], v[188:191], v[28:31]
	v_mfma_f32_16x16x32_bf16 v[24:27], v[172:175], v[188:191], v[24:27]
	v_mfma_f32_16x16x32_bf16 v[12:15], v[148:151], v[196:199], v[12:15]
	v_mfma_f32_16x16x32_bf16 v[8:11], v[172:175], v[196:199], v[8:11]
	v_mfma_f32_16x16x32_bf16 v[4:7], v[148:151], v[204:207], v[4:7]
	v_mfma_f32_16x16x32_bf16 v[0:3], v[172:175], v[204:207], v[0:3]
	s_setprio 0
	s_barrier
	s_add_i32 s68, 0, 0x18000
	s_add_i32 s83, 0, 0x1c000
	v_add_u32_e32 v140, s68, v213
	v_add_u32_e32 v172, s83, v213
	ds_read_b128 v[128:131], v140
	ds_read_b128 v[132:135], v140 offset:1024
	ds_read_b128 v[136:139], v140 offset:2048
	ds_read_b128 v[140:143], v140 offset:3072
	ds_read_b128 v[144:147], v172
	ds_read_b128 v[148:151], v172 offset:1024
	ds_read_b128 v[168:171], v172 offset:2048
	ds_read_b128 v[172:175], v172 offset:3072
	s_add_u32 s62, s62, 0x40000
	s_addc_u32 s63, s63, 0
	s_mov_b32 m0, s66
	ds_read_b128 v[176:179], v216 offset:32768
	ds_read_b128 v[180:183], v216 offset:33792
	ds_read_b128 v[184:187], v216 offset:34816
	ds_read_b128 v[188:191], v216 offset:35840
	ds_read_b128 v[192:195], v216 offset:36864
	ds_read_b128 v[196:199], v216 offset:37888
	ds_read_b128 v[200:203], v216 offset:38912
	ds_read_b128 v[204:207], v216 offset:39936
	global_load_lds_dwordx4 v158, s[62:63]
	s_mov_b32 m0, s67
	s_nop 0
	global_load_lds_dwordx4 v154, s[62:63]
	s_waitcnt vmcnt(8)
	s_waitcnt lgkmcnt(0)
	s_barrier
	s_setprio 1
	v_mfma_f32_16x16x32_bf16 v[124:127], v[128:131], v[176:179], v[124:127]
	v_mfma_f32_16x16x32_bf16 v[120:123], v[136:139], v[176:179], v[120:123]
	v_mfma_f32_16x16x32_bf16 v[116:119], v[128:131], v[184:187], v[116:119]
	v_mfma_f32_16x16x32_bf16 v[112:115], v[136:139], v[184:187], v[112:115]
	v_mfma_f32_16x16x32_bf16 v[108:111], v[128:131], v[192:195], v[108:111]
	v_mfma_f32_16x16x32_bf16 v[100:103], v[136:139], v[192:195], v[100:103]
	v_mfma_f32_16x16x32_bf16 v[88:91], v[128:131], v[200:203], v[88:91]
	v_mfma_f32_16x16x32_bf16 v[80:83], v[136:139], v[200:203], v[80:83]
	v_mfma_f32_16x16x32_bf16 v[124:127], v[132:135], v[180:183], v[124:127]
	v_mfma_f32_16x16x32_bf16 v[120:123], v[140:143], v[180:183], v[120:123]
	v_mfma_f32_16x16x32_bf16 v[116:119], v[132:135], v[188:191], v[116:119]
	v_mfma_f32_16x16x32_bf16 v[112:115], v[140:143], v[188:191], v[112:115]
	v_mfma_f32_16x16x32_bf16 v[108:111], v[132:135], v[196:199], v[108:111]
	v_mfma_f32_16x16x32_bf16 v[100:103], v[140:143], v[196:199], v[100:103]
	v_mfma_f32_16x16x32_bf16 v[88:91], v[132:135], v[204:207], v[88:91]
	v_mfma_f32_16x16x32_bf16 v[80:83], v[140:143], v[204:207], v[80:83]
	s_setprio 0
	s_setprio 1
	v_mfma_f32_16x16x32_bf16 v[104:107], v[144:147], v[176:179], v[104:107]
	v_mfma_f32_16x16x32_bf16 v[96:99], v[168:171], v[176:179], v[96:99]
	v_mfma_f32_16x16x32_bf16 v[92:95], v[144:147], v[184:187], v[92:95]
	v_mfma_f32_16x16x32_bf16 v[84:87], v[168:171], v[184:187], v[84:87]
	v_mfma_f32_16x16x32_bf16 v[76:79], v[144:147], v[192:195], v[76:79]
	v_mfma_f32_16x16x32_bf16 v[72:75], v[168:171], v[192:195], v[72:75]
	v_mfma_f32_16x16x32_bf16 v[68:71], v[144:147], v[200:203], v[68:71]
	v_mfma_f32_16x16x32_bf16 v[64:67], v[168:171], v[200:203], v[64:67]
	v_mfma_f32_16x16x32_bf16 v[104:107], v[148:151], v[180:183], v[104:107]
	v_mfma_f32_16x16x32_bf16 v[96:99], v[172:175], v[180:183], v[96:99]
	v_mfma_f32_16x16x32_bf16 v[92:95], v[148:151], v[188:191], v[92:95]
	v_mfma_f32_16x16x32_bf16 v[84:87], v[172:175], v[188:191], v[84:87]
	v_mfma_f32_16x16x32_bf16 v[76:79], v[148:151], v[196:199], v[76:79]
	v_mfma_f32_16x16x32_bf16 v[72:75], v[172:175], v[196:199], v[72:75]
	v_mfma_f32_16x16x32_bf16 v[68:71], v[148:151], v[204:207], v[68:71]
	v_mfma_f32_16x16x32_bf16 v[64:67], v[172:175], v[204:207], v[64:67]
	s_setprio 0
	s_barrier
	s_add_i32 s62, s68, s33
	v_lshl_add_u64 v[208:209], v[208:209], 0, s[42:43]
	s_mov_b32 m0, s62
	ds_read_b128 v[176:179], v216 offset:49152
	ds_read_b128 v[180:183], v216 offset:50176
	ds_read_b128 v[184:187], v216 offset:51200
	ds_read_b128 v[188:191], v216 offset:52224
	ds_read_b128 v[192:195], v216 offset:53248
	ds_read_b128 v[196:199], v216 offset:54272
	ds_read_b128 v[200:203], v216 offset:55296
	ds_read_b128 v[204:207], v216 offset:56320
	global_load_lds_dwordx4 v[208:209], off
	s_add_i32 m0, s62, 0x2000
	s_add_u32 s6, s6, 0x40080
	v_lshl_add_u64 v[208:209], v[220:221], 0, s[42:43]
	s_addc_u32 s7, s7, 0
	s_add_i32 s62, s83, s33
	global_load_lds_dwordx4 v[208:209], off
	s_mov_b32 m0, s62
	s_nop 0
	global_load_lds_dwordx4 v156, s[6:7]
	s_add_i32 m0, s62, 0x2000
	s_nop 0
	global_load_lds_dwordx4 v152, s[6:7]
	v_lshl_add_u64 v[208:209], v[222:223], 0, s[42:43]
	s_mov_b32 m0, s75
	s_nop 0
	global_load_lds_dwordx4 v[208:209], off
	v_lshl_add_u64 v[208:209], v[224:225], 0, s[42:43]
	s_mov_b32 m0, s76
	s_nop 0
	global_load_lds_dwordx4 v[208:209], off
	s_waitcnt vmcnt(8)
	s_waitcnt lgkmcnt(0)
	s_barrier
	s_setprio 1
	v_mfma_f32_16x16x32_bf16 v[60:63], v[128:131], v[176:179], v[60:63]
	v_mfma_f32_16x16x32_bf16 v[56:59], v[136:139], v[176:179], v[56:59]
	v_mfma_f32_16x16x32_bf16 v[52:55], v[128:131], v[184:187], v[52:55]
	v_mfma_f32_16x16x32_bf16 v[48:51], v[136:139], v[184:187], v[48:51]
	v_mfma_f32_16x16x32_bf16 v[40:43], v[128:131], v[192:195], v[40:43]
	v_mfma_f32_16x16x32_bf16 v[32:35], v[136:139], v[192:195], v[32:35]
	v_mfma_f32_16x16x32_bf16 v[20:23], v[128:131], v[200:203], v[20:23]
	v_mfma_f32_16x16x32_bf16 v[16:19], v[136:139], v[200:203], v[16:19]
	v_mfma_f32_16x16x32_bf16 v[60:63], v[132:135], v[180:183], v[60:63]
	v_mfma_f32_16x16x32_bf16 v[56:59], v[140:143], v[180:183], v[56:59]
	v_mfma_f32_16x16x32_bf16 v[52:55], v[132:135], v[188:191], v[52:55]
	v_mfma_f32_16x16x32_bf16 v[48:51], v[140:143], v[188:191], v[48:51]
	v_mfma_f32_16x16x32_bf16 v[40:43], v[132:135], v[196:199], v[40:43]
	v_mfma_f32_16x16x32_bf16 v[32:35], v[140:143], v[196:199], v[32:35]
	v_mfma_f32_16x16x32_bf16 v[20:23], v[132:135], v[204:207], v[20:23]
	v_mfma_f32_16x16x32_bf16 v[16:19], v[140:143], v[204:207], v[16:19]
	s_setprio 0
	s_setprio 1
	v_mfma_f32_16x16x32_bf16 v[44:47], v[144:147], v[176:179], v[44:47]
	v_mfma_f32_16x16x32_bf16 v[36:39], v[168:171], v[176:179], v[36:39]
	v_mfma_f32_16x16x32_bf16 v[28:31], v[144:147], v[184:187], v[28:31]
	v_mfma_f32_16x16x32_bf16 v[24:27], v[168:171], v[184:187], v[24:27]
	v_mfma_f32_16x16x32_bf16 v[12:15], v[144:147], v[192:195], v[12:15]
	v_mfma_f32_16x16x32_bf16 v[8:11], v[168:171], v[192:195], v[8:11]
	v_mfma_f32_16x16x32_bf16 v[4:7], v[144:147], v[200:203], v[4:7]
	v_mfma_f32_16x16x32_bf16 v[0:3], v[168:171], v[200:203], v[0:3]
	v_mfma_f32_16x16x32_bf16 v[44:47], v[148:151], v[180:183], v[44:47]
	v_mfma_f32_16x16x32_bf16 v[36:39], v[172:175], v[180:183], v[36:39]
	v_mfma_f32_16x16x32_bf16 v[28:31], v[148:151], v[188:191], v[28:31]
	v_mfma_f32_16x16x32_bf16 v[24:27], v[172:175], v[188:191], v[24:27]
	v_mfma_f32_16x16x32_bf16 v[12:15], v[148:151], v[196:199], v[12:15]
	v_mfma_f32_16x16x32_bf16 v[8:11], v[172:175], v[196:199], v[8:11]
	v_mfma_f32_16x16x32_bf16 v[4:7], v[148:151], v[204:207], v[4:7]
	v_mfma_f32_16x16x32_bf16 v[0:3], v[172:175], v[204:207], v[0:3]
	s_setprio 0
	s_barrier
	s_add_i32 s57, s57, 2
	s_add_u32 s4, s4, 0x100
	s_addc_u32 s5, s5, 0
	s_add_u32 s28, s28, 0x100
	s_addc_u32 s55, s55, 0
	s_cmp_gt_u32 s57, 13
	s_cbranch_scc0 .LBB0_704
	s_and_b64 vcc, exec, s[44:45]
	s_cbranch_vccz .LBB0_707
	s_barrier

.LBB0_862:
	ds_read_b128 v[152:155], v159
	ds_read_b128 v[164:167], v159 offset:1024
	ds_read_b128 v[168:171], v159 offset:2048
	ds_read_b128 v[172:175], v159 offset:3072
	ds_read_b128 v[176:179], v160
	ds_read_b128 v[180:183], v160 offset:1024
	ds_read_b128 v[184:187], v160 offset:2048
	ds_read_b128 v[188:191], v160 offset:3072
	s_add_u32 s4, s40, 0x100
	s_addc_u32 s5, s41, 0
	s_cmp_eq_u32 s58, 2
	s_cselect_b32 s45, s35, s5
	s_cselect_b32 s44, s34, s4
	s_cselect_b32 s43, s37, s57
	s_cselect_b32 s42, s36, s56
	s_add_i32 m0, s11, 0xc000
	ds_read_b128 v[192:195], v161
	ds_read_b128 v[196:199], v161 offset:1024
	ds_read_b128 v[200:203], v161 offset:2048
	ds_read_b128 v[204:207], v161 offset:3072
	ds_read_b128 v[212:215], v161 offset:4096
	ds_read_b128 v[216:219], v161 offset:5120
	ds_read_b128 v[220:223], v161 offset:6144
	ds_read_b128 v[224:227], v161 offset:7168
	global_load_lds_dwordx4 v144, s[40:41]
	s_add_i32 m0, s11, 0xe000
	s_nop 0
	global_load_lds_dwordx4 v146, s[40:41]
	s_waitcnt vmcnt(8)
	s_waitcnt lgkmcnt(0)
	s_barrier
	s_setprio 1
	v_mfma_f32_16x16x32_bf16 v[124:127], v[152:155], v[192:195], v[124:127]
	v_mfma_f32_16x16x32_bf16 v[120:123], v[168:171], v[192:195], v[120:123]
	v_mfma_f32_16x16x32_bf16 v[108:111], v[152:155], v[200:203], v[108:111]
	v_mfma_f32_16x16x32_bf16 v[104:107], v[168:171], v[200:203], v[104:107]
	v_mfma_f32_16x16x32_bf16 v[92:95], v[152:155], v[212:215], v[92:95]
	v_mfma_f32_16x16x32_bf16 v[88:91], v[168:171], v[212:215], v[88:91]
	v_mfma_f32_16x16x32_bf16 v[76:79], v[152:155], v[220:223], v[76:79]
	v_mfma_f32_16x16x32_bf16 v[72:75], v[168:171], v[220:223], v[72:75]
	v_mfma_f32_16x16x32_bf16 v[124:127], v[164:167], v[196:199], v[124:127]
	v_mfma_f32_16x16x32_bf16 v[120:123], v[172:175], v[196:199], v[120:123]
	v_mfma_f32_16x16x32_bf16 v[108:111], v[164:167], v[204:207], v[108:111]
	v_mfma_f32_16x16x32_bf16 v[104:107], v[172:175], v[204:207], v[104:107]
	v_mfma_f32_16x16x32_bf16 v[92:95], v[164:167], v[216:219], v[92:95]
	v_mfma_f32_16x16x32_bf16 v[88:91], v[172:175], v[216:219], v[88:91]
	v_mfma_f32_16x16x32_bf16 v[76:79], v[164:167], v[224:227], v[76:79]
	v_mfma_f32_16x16x32_bf16 v[72:75], v[172:175], v[224:227], v[72:75]
	s_setprio 0
	s_setprio 1
	v_mfma_f32_16x16x32_bf16 v[116:119], v[176:179], v[192:195], v[116:119]
	v_mfma_f32_16x16x32_bf16 v[112:115], v[184:187], v[192:195], v[112:115]
	v_mfma_f32_16x16x32_bf16 v[100:103], v[176:179], v[200:203], v[100:103]
	v_mfma_f32_16x16x32_bf16 v[96:99], v[184:187], v[200:203], v[96:99]
	v_mfma_f32_16x16x32_bf16 v[84:87], v[176:179], v[212:215], v[84:87]
	v_mfma_f32_16x16x32_bf16 v[80:83], v[184:187], v[212:215], v[80:83]
	v_mfma_f32_16x16x32_bf16 v[68:71], v[176:179], v[220:223], v[68:71]
	v_mfma_f32_16x16x32_bf16 v[64:67], v[184:187], v[220:223], v[64:67]
	v_mfma_f32_16x16x32_bf16 v[116:119], v[180:183], v[196:199], v[116:119]
	v_mfma_f32_16x16x32_bf16 v[112:115], v[188:191], v[196:199], v[112:115]
	v_mfma_f32_16x16x32_bf16 v[100:103], v[180:183], v[204:207], v[100:103]
	v_mfma_f32_16x16x32_bf16 v[96:99], v[188:191], v[204:207], v[96:99]
	v_mfma_f32_16x16x32_bf16 v[84:87], v[180:183], v[216:219], v[84:87]
	v_mfma_f32_16x16x32_bf16 v[80:83], v[188:191], v[216:219], v[80:83]
	v_mfma_f32_16x16x32_bf16 v[68:71], v[180:183], v[224:227], v[68:71]
	v_mfma_f32_16x16x32_bf16 v[64:67], v[188:191], v[224:227], v[64:67]
	s_setprio 0
	s_barrier
	s_add_i32 s40, s48, s10
	v_lshl_add_u64 v[156:157], s[42:43], 0, v[130:131]
	s_mov_b32 m0, s40
	ds_read_b128 v[192:195], v161 offset:16384
	ds_read_b128 v[196:199], v161 offset:17408
	ds_read_b128 v[200:203], v161 offset:18432
	ds_read_b128 v[204:207], v161 offset:19456
	ds_read_b128 v[212:215], v161 offset:20480
	ds_read_b128 v[216:219], v161 offset:21504
	ds_read_b128 v[220:223], v161 offset:22528
	ds_read_b128 v[224:227], v161 offset:23552
	global_load_lds_dwordx4 v[156:157], off
	s_add_i32 m0, s40, 0x2000
	s_add_u32 s40, s42, 0x18000
	v_lshl_add_u64 v[208:209], s[42:43], 0, v[134:135]
	s_addc_u32 s41, s43, 0
	s_add_i32 s59, s49, s10
	global_load_lds_dwordx4 v[208:209], off
	s_mov_b32 m0, s59
	v_lshl_add_u64 v[230:231], s[44:45], 0, v[132:133]
	global_load_lds_dwordx4 v130, s[40:41]
	s_add_i32 m0, s59, 0x2000
	s_nop 0
	global_load_lds_dwordx4 v134, s[40:41]
	v_lshl_add_u64 v[228:229], s[44:45], 0, v[128:129]
	s_mov_b32 m0, s11
	s_nop 0
	global_load_lds_dwordx4 v[228:229], off
	s_mov_b32 m0, s14
	s_nop 0
	global_load_lds_dwordx4 v[230:231], off
	s_waitcnt vmcnt(8)
	s_waitcnt lgkmcnt(0)
	s_barrier
	s_setprio 1
	v_mfma_f32_16x16x32_bf16 v[60:63], v[152:155], v[192:195], v[60:63]
	v_mfma_f32_16x16x32_bf16 v[56:59], v[168:171], v[192:195], v[56:59]
	v_mfma_f32_16x16x32_bf16 v[44:47], v[152:155], v[200:203], v[44:47]
	v_mfma_f32_16x16x32_bf16 v[40:43], v[168:171], v[200:203], v[40:43]
	v_mfma_f32_16x16x32_bf16 v[28:31], v[152:155], v[212:215], v[28:31]
	v_mfma_f32_16x16x32_bf16 v[24:27], v[168:171], v[212:215], v[24:27]
	v_mfma_f32_16x16x32_bf16 v[12:15], v[152:155], v[220:223], v[12:15]
	v_mfma_f32_16x16x32_bf16 v[8:11], v[168:171], v[220:223], v[8:11]
	v_mfma_f32_16x16x32_bf16 v[60:63], v[164:167], v[196:199], v[60:63]
	v_mfma_f32_16x16x32_bf16 v[56:59], v[172:175], v[196:199], v[56:59]
	v_mfma_f32_16x16x32_bf16 v[44:47], v[164:167], v[204:207], v[44:47]
	v_mfma_f32_16x16x32_bf16 v[40:43], v[172:175], v[204:207], v[40:43]
	v_mfma_f32_16x16x32_bf16 v[28:31], v[164:167], v[216:219], v[28:31]
	v_mfma_f32_16x16x32_bf16 v[24:27], v[172:175], v[216:219], v[24:27]
	v_mfma_f32_16x16x32_bf16 v[12:15], v[164:167], v[224:227], v[12:15]
	v_mfma_f32_16x16x32_bf16 v[8:11], v[172:175], v[224:227], v[8:11]
	s_setprio 0
	s_setprio 1
	v_mfma_f32_16x16x32_bf16 v[52:55], v[176:179], v[192:195], v[52:55]
	v_mfma_f32_16x16x32_bf16 v[48:51], v[184:187], v[192:195], v[48:51]
	v_mfma_f32_16x16x32_bf16 v[36:39], v[176:179], v[200:203], v[36:39]
	v_mfma_f32_16x16x32_bf16 v[32:35], v[184:187], v[200:203], v[32:35]
	v_mfma_f32_16x16x32_bf16 v[20:23], v[176:179], v[212:215], v[20:23]
	v_mfma_f32_16x16x32_bf16 v[16:19], v[184:187], v[212:215], v[16:19]
	v_mfma_f32_16x16x32_bf16 v[4:7], v[176:179], v[220:223], v[4:7]
	v_mfma_f32_16x16x32_bf16 v[0:3], v[184:187], v[220:223], v[0:3]
	v_mfma_f32_16x16x32_bf16 v[52:55], v[180:183], v[196:199], v[52:55]
	v_mfma_f32_16x16x32_bf16 v[48:51], v[188:191], v[196:199], v[48:51]
	v_mfma_f32_16x16x32_bf16 v[36:39], v[180:183], v[204:207], v[36:39]
	v_mfma_f32_16x16x32_bf16 v[32:35], v[188:191], v[204:207], v[32:35]
	v_mfma_f32_16x16x32_bf16 v[20:23], v[180:183], v[216:219], v[20:23]
	v_mfma_f32_16x16x32_bf16 v[16:19], v[188:191], v[216:219], v[16:19]
	v_mfma_f32_16x16x32_bf16 v[4:7], v[180:183], v[224:227], v[4:7]
	v_mfma_f32_16x16x32_bf16 v[0:3], v[188:191], v[224:227], v[0:3]
	s_setprio 0
	s_barrier
	s_add_i32 s59, 0, 0x18000
	v_add_u32_e32 v163, s59, v158
	s_add_i32 s60, 0, 0x1c000
	ds_read_b128 v[152:155], v163
	ds_read_b128 v[164:167], v163 offset:1024
	ds_read_b128 v[168:171], v163 offset:2048
	ds_read_b128 v[172:175], v163 offset:3072
	v_add_u32_e32 v163, s60, v158
	ds_read_b128 v[176:179], v163
	ds_read_b128 v[180:183], v163 offset:1024
	ds_read_b128 v[184:187], v163 offset:2048
	ds_read_b128 v[188:191], v163 offset:3072
	s_add_u32 s40, s44, 0x18000
	s_addc_u32 s41, s45, 0
	s_mov_b32 m0, s15
	ds_read_b128 v[192:195], v161 offset:32768
	ds_read_b128 v[196:199], v161 offset:33792
	ds_read_b128 v[200:203], v161 offset:34816
	ds_read_b128 v[204:207], v161 offset:35840
	ds_read_b128 v[212:215], v161 offset:36864
	ds_read_b128 v[216:219], v161 offset:37888
	ds_read_b128 v[220:223], v161 offset:38912
	ds_read_b128 v[224:227], v161 offset:39936
	global_load_lds_dwordx4 v128, s[40:41]
	s_mov_b32 m0, s28
	s_nop 0
	global_load_lds_dwordx4 v132, s[40:41]
	s_waitcnt vmcnt(8)
	s_waitcnt lgkmcnt(0)
	s_barrier
	s_setprio 1
	v_mfma_f32_16x16x32_bf16 v[124:127], v[152:155], v[192:195], v[124:127]
	v_mfma_f32_16x16x32_bf16 v[120:123], v[168:171], v[192:195], v[120:123]
	v_mfma_f32_16x16x32_bf16 v[108:111], v[152:155], v[200:203], v[108:111]
	v_mfma_f32_16x16x32_bf16 v[104:107], v[168:171], v[200:203], v[104:107]
	v_mfma_f32_16x16x32_bf16 v[92:95], v[152:155], v[212:215], v[92:95]
	v_mfma_f32_16x16x32_bf16 v[88:91], v[168:171], v[212:215], v[88:91]
	v_mfma_f32_16x16x32_bf16 v[76:79], v[152:155], v[220:223], v[76:79]
	v_mfma_f32_16x16x32_bf16 v[72:75], v[168:171], v[220:223], v[72:75]
	v_mfma_f32_16x16x32_bf16 v[124:127], v[164:167], v[196:199], v[124:127]
	v_mfma_f32_16x16x32_bf16 v[120:123], v[172:175], v[196:199], v[120:123]
	v_mfma_f32_16x16x32_bf16 v[108:111], v[164:167], v[204:207], v[108:111]
	v_mfma_f32_16x16x32_bf16 v[104:107], v[172:175], v[204:207], v[104:107]
	v_mfma_f32_16x16x32_bf16 v[92:95], v[164:167], v[216:219], v[92:95]
	v_mfma_f32_16x16x32_bf16 v[88:91], v[172:175], v[216:219], v[88:91]
	v_mfma_f32_16x16x32_bf16 v[76:79], v[164:167], v[224:227], v[76:79]
	v_mfma_f32_16x16x32_bf16 v[72:75], v[172:175], v[224:227], v[72:75]
	s_setprio 0
	s_setprio 1
	v_mfma_f32_16x16x32_bf16 v[116:119], v[176:179], v[192:195], v[116:119]
	v_mfma_f32_16x16x32_bf16 v[112:115], v[184:187], v[192:195], v[112:115]
	v_mfma_f32_16x16x32_bf16 v[100:103], v[176:179], v[200:203], v[100:103]
	v_mfma_f32_16x16x32_bf16 v[96:99], v[184:187], v[200:203], v[96:99]
	v_mfma_f32_16x16x32_bf16 v[84:87], v[176:179], v[212:215], v[84:87]
	v_mfma_f32_16x16x32_bf16 v[80:83], v[184:187], v[212:215], v[80:83]
	v_mfma_f32_16x16x32_bf16 v[68:71], v[176:179], v[220:223], v[68:71]
	v_mfma_f32_16x16x32_bf16 v[64:67], v[184:187], v[220:223], v[64:67]
	v_mfma_f32_16x16x32_bf16 v[116:119], v[180:183], v[196:199], v[116:119]
	v_mfma_f32_16x16x32_bf16 v[112:115], v[188:191], v[196:199], v[112:115]
	v_mfma_f32_16x16x32_bf16 v[100:103], v[180:183], v[204:207], v[100:103]
	v_mfma_f32_16x16x32_bf16 v[96:99], v[188:191], v[204:207], v[96:99]
	v_mfma_f32_16x16x32_bf16 v[84:87], v[180:183], v[216:219], v[84:87]
	v_mfma_f32_16x16x32_bf16 v[80:83], v[188:191], v[216:219], v[80:83]
	v_mfma_f32_16x16x32_bf16 v[68:71], v[180:183], v[224:227], v[68:71]
	v_mfma_f32_16x16x32_bf16 v[64:67], v[188:191], v[224:227], v[64:67]
	s_setprio 0
	s_barrier
	s_add_i32 s40, s59, s10
	v_lshl_add_u64 v[156:157], v[156:157], 0, s[8:9]
	s_mov_b32 m0, s40
	ds_read_b128 v[192:195], v161 offset:49152
	ds_read_b128 v[196:199], v161 offset:50176
	ds_read_b128 v[200:203], v161 offset:51200
	ds_read_b128 v[204:207], v161 offset:52224
	ds_read_b128 v[212:215], v161 offset:53248
	ds_read_b128 v[216:219], v161 offset:54272
	ds_read_b128 v[220:223], v161 offset:55296
	ds_read_b128 v[224:227], v161 offset:56320
	global_load_lds_dwordx4 v[156:157], off
	s_add_i32 m0, s40, 0x2000
	s_add_u32 s40, s42, 0x18080
	v_lshl_add_u64 v[156:157], v[208:209], 0, s[8:9]
	s_addc_u32 s41, s43, 0
	s_add_i32 s42, s60, s10
	global_load_lds_dwordx4 v[156:157], off
	s_mov_b32 m0, s42
	s_nop 0
	global_load_lds_dwordx4 v130, s[40:41]
	s_add_i32 m0, s42, 0x2000
	s_nop 0
	global_load_lds_dwordx4 v134, s[40:41]
	v_lshl_add_u64 v[156:157], v[228:229], 0, s[8:9]
	s_mov_b32 m0, s33
	s_nop 0
	global_load_lds_dwordx4 v[156:157], off
	v_lshl_add_u64 v[156:157], v[230:231], 0, s[8:9]
	s_mov_b32 m0, s46
	s_nop 0
	global_load_lds_dwordx4 v[156:157], off
	s_waitcnt vmcnt(8)
	s_waitcnt lgkmcnt(0)
	s_barrier
	s_setprio 1
	v_mfma_f32_16x16x32_bf16 v[60:63], v[152:155], v[192:195], v[60:63]
	v_mfma_f32_16x16x32_bf16 v[56:59], v[168:171], v[192:195], v[56:59]
	v_mfma_f32_16x16x32_bf16 v[44:47], v[152:155], v[200:203], v[44:47]
	v_mfma_f32_16x16x32_bf16 v[40:43], v[168:171], v[200:203], v[40:43]
	v_mfma_f32_16x16x32_bf16 v[28:31], v[152:155], v[212:215], v[28:31]
	v_mfma_f32_16x16x32_bf16 v[24:27], v[168:171], v[212:215], v[24:27]
	v_mfma_f32_16x16x32_bf16 v[12:15], v[152:155], v[220:223], v[12:15]
	v_mfma_f32_16x16x32_bf16 v[8:11], v[168:171], v[220:223], v[8:11]
	v_mfma_f32_16x16x32_bf16 v[60:63], v[164:167], v[196:199], v[60:63]
	v_mfma_f32_16x16x32_bf16 v[56:59], v[172:175], v[196:199], v[56:59]
	v_mfma_f32_16x16x32_bf16 v[44:47], v[164:167], v[204:207], v[44:47]
	v_mfma_f32_16x16x32_bf16 v[40:43], v[172:175], v[204:207], v[40:43]
	v_mfma_f32_16x16x32_bf16 v[28:31], v[164:167], v[216:219], v[28:31]
	v_mfma_f32_16x16x32_bf16 v[24:27], v[172:175], v[216:219], v[24:27]
	v_mfma_f32_16x16x32_bf16 v[12:15], v[164:167], v[224:227], v[12:15]
	v_mfma_f32_16x16x32_bf16 v[8:11], v[172:175], v[224:227], v[8:11]
	s_setprio 0
	s_setprio 1
	v_mfma_f32_16x16x32_bf16 v[52:55], v[176:179], v[192:195], v[52:55]
	v_mfma_f32_16x16x32_bf16 v[48:51], v[184:187], v[192:195], v[48:51]
	v_mfma_f32_16x16x32_bf16 v[36:39], v[176:179], v[200:203], v[36:39]
	v_mfma_f32_16x16x32_bf16 v[32:35], v[184:187], v[200:203], v[32:35]
	v_mfma_f32_16x16x32_bf16 v[20:23], v[176:179], v[212:215], v[20:23]
	v_mfma_f32_16x16x32_bf16 v[16:19], v[184:187], v[212:215], v[16:19]
	v_mfma_f32_16x16x32_bf16 v[4:7], v[176:179], v[220:223], v[4:7]
	v_mfma_f32_16x16x32_bf16 v[0:3], v[184:187], v[220:223], v[0:3]
	v_mfma_f32_16x16x32_bf16 v[52:55], v[180:183], v[196:199], v[52:55]
	v_mfma_f32_16x16x32_bf16 v[48:51], v[188:191], v[196:199], v[48:51]
	v_mfma_f32_16x16x32_bf16 v[36:39], v[180:183], v[204:207], v[36:39]
	v_mfma_f32_16x16x32_bf16 v[32:35], v[188:191], v[204:207], v[32:35]
	v_mfma_f32_16x16x32_bf16 v[20:23], v[180:183], v[216:219], v[20:23]
	v_mfma_f32_16x16x32_bf16 v[16:19], v[188:191], v[216:219], v[16:19]
	v_mfma_f32_16x16x32_bf16 v[4:7], v[180:183], v[224:227], v[4:7]
	v_mfma_f32_16x16x32_bf16 v[0:3], v[188:191], v[224:227], v[0:3]
	s_setprio 0
	s_barrier
	s_add_i32 s58, s58, 2
	s_add_u32 s56, s56, 0x100
	s_addc_u32 s57, s57, 0
	s_cmp_gt_u32 s58, 3
	s_mov_b64 s[40:41], s[4:5]
	s_cbranch_scc0 .LBB0_862
	s_and_b64 vcc, exec, s[20:21]
	s_cbranch_vccz .LBB0_865
	s_barrier

.LBB0_894:
	s_add_u32 s46, s34, s40
	s_addc_u32 s47, s35, s41
	s_add_u32 s44, s46, 0x100
	s_addc_u32 s45, s47, 0
	s_and_b64 s[42:43], s[38:39], exec
	s_cselect_b32 s43, s19, s45
	s_cselect_b32 s42, s53, s44
	s_add_u32 s40, s30, s40
	s_addc_u32 s41, s31, s41
	s_add_u32 s40, s40, 0x100
	s_addc_u32 s41, s41, 0
	s_and_b64 s[38:39], s[38:39], exec
	s_cselect_b32 s45, s9, s41
	s_cselect_b32 s44, s54, s40
	s_add_u32 s48, s46, 0x10080
	ds_read_b128 v[144:147], v150
	ds_read_b128 v[154:157], v150 offset:1024
	ds_read_b128 v[158:161], v150 offset:2048
	ds_read_b128 v[162:165], v150 offset:3072
	ds_read_b128 v[166:169], v151
	ds_read_b128 v[170:173], v151 offset:1024
	ds_read_b128 v[174:177], v151 offset:2048
	ds_read_b128 v[178:181], v151 offset:3072
	s_addc_u32 s49, s47, 0
	s_add_i32 s64, s50, s10
	s_add_i32 m0, s11, 0xc000
	s_add_i32 s65, s11, 0xe000
	s_add_i32 s61, s64, 0x2000
	s_add_u32 s46, s44, 0x10000
	s_addc_u32 s47, s45, 0
	s_add_i32 s63, s51, s10
	s_add_i32 s62, s63, 0x2000
	s_add_i32 s60, 0, 0x18000
	s_add_i32 s59, 0, 0x1c000
	s_add_u32 s40, s42, 0x10000
	s_addc_u32 s41, s43, 0
	s_add_i32 s58, s60, s10
	s_add_i32 s56, s58, 0x2000
	s_add_u32 s38, s44, 0x10080
	s_addc_u32 s39, s45, 0
	s_add_i32 s57, s59, s10
	s_add_i32 s55, s57, 0x2000
	ds_read_b128 v[182:185], v152
	ds_read_b128 v[186:189], v152 offset:1024
	ds_read_b128 v[190:193], v152 offset:2048
	ds_read_b128 v[194:197], v152 offset:3072
	ds_read_b128 v[198:201], v152 offset:4096
	ds_read_b128 v[202:205], v152 offset:5120
	ds_read_b128 v[206:209], v152 offset:6144
	ds_read_b128 v[212:215], v152 offset:7168
	global_load_lds_dwordx4 v134, s[48:49]
	s_mov_b32 m0, s65
	s_nop 0
	global_load_lds_dwordx4 v130, s[48:49]
	s_waitcnt vmcnt(8)
	s_waitcnt lgkmcnt(0)
	s_barrier
	s_setprio 1
	v_mfma_f32_16x16x32_bf16 v[124:127], v[144:147], v[182:185], v[124:127]
	v_mfma_f32_16x16x32_bf16 v[120:123], v[158:161], v[182:185], v[120:123]
	v_mfma_f32_16x16x32_bf16 v[108:111], v[144:147], v[190:193], v[108:111]
	v_mfma_f32_16x16x32_bf16 v[104:107], v[158:161], v[190:193], v[104:107]
	v_mfma_f32_16x16x32_bf16 v[92:95], v[144:147], v[198:201], v[92:95]
	v_mfma_f32_16x16x32_bf16 v[88:91], v[158:161], v[198:201], v[88:91]
	v_mfma_f32_16x16x32_bf16 v[76:79], v[144:147], v[206:209], v[76:79]
	v_mfma_f32_16x16x32_bf16 v[72:75], v[158:161], v[206:209], v[72:75]
	v_mfma_f32_16x16x32_bf16 v[124:127], v[154:157], v[186:189], v[124:127]
	v_mfma_f32_16x16x32_bf16 v[120:123], v[162:165], v[186:189], v[120:123]
	v_mfma_f32_16x16x32_bf16 v[108:111], v[154:157], v[194:197], v[108:111]
	v_mfma_f32_16x16x32_bf16 v[104:107], v[162:165], v[194:197], v[104:107]
	v_mfma_f32_16x16x32_bf16 v[92:95], v[154:157], v[202:205], v[92:95]
	v_mfma_f32_16x16x32_bf16 v[88:91], v[162:165], v[202:205], v[88:91]
	v_mfma_f32_16x16x32_bf16 v[76:79], v[154:157], v[212:215], v[76:79]
	v_mfma_f32_16x16x32_bf16 v[72:75], v[162:165], v[212:215], v[72:75]
	s_setprio 0
	s_setprio 1
	v_mfma_f32_16x16x32_bf16 v[116:119], v[166:169], v[182:185], v[116:119]
	v_mfma_f32_16x16x32_bf16 v[112:115], v[174:177], v[182:185], v[112:115]
	v_mfma_f32_16x16x32_bf16 v[100:103], v[166:169], v[190:193], v[100:103]
	v_mfma_f32_16x16x32_bf16 v[96:99], v[174:177], v[190:193], v[96:99]
	v_mfma_f32_16x16x32_bf16 v[84:87], v[166:169], v[198:201], v[84:87]
	v_mfma_f32_16x16x32_bf16 v[80:83], v[174:177], v[198:201], v[80:83]
	v_mfma_f32_16x16x32_bf16 v[68:71], v[166:169], v[206:209], v[68:71]
	v_mfma_f32_16x16x32_bf16 v[64:67], v[174:177], v[206:209], v[64:67]
	v_mfma_f32_16x16x32_bf16 v[116:119], v[170:173], v[186:189], v[116:119]
	v_mfma_f32_16x16x32_bf16 v[112:115], v[178:181], v[186:189], v[112:115]
	v_mfma_f32_16x16x32_bf16 v[100:103], v[170:173], v[194:197], v[100:103]
	v_mfma_f32_16x16x32_bf16 v[96:99], v[178:181], v[194:197], v[96:99]
	v_mfma_f32_16x16x32_bf16 v[84:87], v[170:173], v[202:205], v[84:87]
	v_mfma_f32_16x16x32_bf16 v[80:83], v[178:181], v[202:205], v[80:83]
	v_mfma_f32_16x16x32_bf16 v[68:71], v[170:173], v[212:215], v[68:71]
	v_mfma_f32_16x16x32_bf16 v[64:67], v[178:181], v[212:215], v[64:67]
	s_setprio 0
	s_barrier
	s_mov_b32 m0, s64
	v_lshl_add_u64 v[216:217], s[44:45], 0, v[132:133]
	ds_read_b128 v[182:185], v152 offset:16384
	ds_read_b128 v[186:189], v152 offset:17408
	ds_read_b128 v[190:193], v152 offset:18432
	ds_read_b128 v[194:197], v152 offset:19456
	ds_read_b128 v[198:201], v152 offset:20480
	ds_read_b128 v[202:205], v152 offset:21504
	ds_read_b128 v[206:209], v152 offset:22528
	ds_read_b128 v[212:215], v152 offset:23552
	global_load_lds_dwordx4 v[216:217], off
	v_lshl_add_u64 v[218:219], s[44:45], 0, v[128:129]
	s_mov_b32 m0, s61
	s_nop 0
	global_load_lds_dwordx4 v[218:219], off
	s_mov_b32 m0, s63
	v_lshl_add_u64 v[222:223], s[42:43], 0, v[130:131]
	global_load_lds_dwordx4 v132, s[46:47]
	s_mov_b32 m0, s62
	s_nop 0
	global_load_lds_dwordx4 v128, s[46:47]
	v_lshl_add_u64 v[220:221], s[42:43], 0, v[134:135]
	s_mov_b32 m0, s11
	s_nop 0
	global_load_lds_dwordx4 v[220:221], off
	s_mov_b32 m0, s14
	s_nop 0
	global_load_lds_dwordx4 v[222:223], off
	s_waitcnt vmcnt(8)
	s_waitcnt lgkmcnt(0)
	s_barrier
	s_setprio 1
	v_mfma_f32_16x16x32_bf16 v[60:63], v[144:147], v[182:185], v[60:63]
	v_mfma_f32_16x16x32_bf16 v[56:59], v[158:161], v[182:185], v[56:59]
	v_mfma_f32_16x16x32_bf16 v[44:47], v[144:147], v[190:193], v[44:47]
	v_mfma_f32_16x16x32_bf16 v[40:43], v[158:161], v[190:193], v[40:43]
	v_mfma_f32_16x16x32_bf16 v[28:31], v[144:147], v[198:201], v[28:31]
	v_mfma_f32_16x16x32_bf16 v[24:27], v[158:161], v[198:201], v[24:27]
	v_mfma_f32_16x16x32_bf16 v[12:15], v[144:147], v[206:209], v[12:15]
	v_mfma_f32_16x16x32_bf16 v[8:11], v[158:161], v[206:209], v[8:11]
	v_mfma_f32_16x16x32_bf16 v[60:63], v[154:157], v[186:189], v[60:63]
	v_mfma_f32_16x16x32_bf16 v[56:59], v[162:165], v[186:189], v[56:59]
	v_mfma_f32_16x16x32_bf16 v[44:47], v[154:157], v[194:197], v[44:47]
	v_mfma_f32_16x16x32_bf16 v[40:43], v[162:165], v[194:197], v[40:43]
	v_mfma_f32_16x16x32_bf16 v[28:31], v[154:157], v[202:205], v[28:31]
	v_mfma_f32_16x16x32_bf16 v[24:27], v[162:165], v[202:205], v[24:27]
	v_mfma_f32_16x16x32_bf16 v[12:15], v[154:157], v[212:215], v[12:15]
	v_mfma_f32_16x16x32_bf16 v[8:11], v[162:165], v[212:215], v[8:11]
	s_setprio 0
	s_setprio 1
	v_mfma_f32_16x16x32_bf16 v[52:55], v[166:169], v[182:185], v[52:55]
	v_mfma_f32_16x16x32_bf16 v[48:51], v[174:177], v[182:185], v[48:51]
	v_mfma_f32_16x16x32_bf16 v[36:39], v[166:169], v[190:193], v[36:39]
	v_mfma_f32_16x16x32_bf16 v[32:35], v[174:177], v[190:193], v[32:35]
	v_mfma_f32_16x16x32_bf16 v[20:23], v[166:169], v[198:201], v[20:23]
	v_mfma_f32_16x16x32_bf16 v[16:19], v[174:177], v[198:201], v[16:19]
	v_mfma_f32_16x16x32_bf16 v[4:7], v[166:169], v[206:209], v[4:7]
	v_mfma_f32_16x16x32_bf16 v[0:3], v[174:177], v[206:209], v[0:3]
	v_mfma_f32_16x16x32_bf16 v[52:55], v[170:173], v[186:189], v[52:55]
	v_mfma_f32_16x16x32_bf16 v[48:51], v[178:181], v[186:189], v[48:51]
	v_mfma_f32_16x16x32_bf16 v[36:39], v[170:173], v[194:197], v[36:39]
	v_mfma_f32_16x16x32_bf16 v[32:35], v[178:181], v[194:197], v[32:35]
	v_mfma_f32_16x16x32_bf16 v[20:23], v[170:173], v[202:205], v[20:23]
	v_mfma_f32_16x16x32_bf16 v[16:19], v[178:181], v[202:205], v[16:19]
	v_mfma_f32_16x16x32_bf16 v[4:7], v[170:173], v[212:215], v[4:7]
	v_mfma_f32_16x16x32_bf16 v[0:3], v[178:181], v[212:215], v[0:3]
	s_setprio 0
	s_barrier
	v_add_u32_e32 v162, s60, v149
	v_add_u32_e32 v178, s59, v149
	ds_read_b128 v[144:147], v162
	ds_read_b128 v[154:157], v162 offset:1024
	ds_read_b128 v[158:161], v162 offset:2048
	ds_read_b128 v[162:165], v162 offset:3072
	ds_read_b128 v[166:169], v178
	ds_read_b128 v[170:173], v178 offset:1024
	ds_read_b128 v[174:177], v178 offset:2048
	ds_read_b128 v[178:181], v178 offset:3072
	s_mov_b32 m0, s15
	ds_read_b128 v[182:185], v152 offset:32768
	ds_read_b128 v[186:189], v152 offset:33792
	ds_read_b128 v[190:193], v152 offset:34816
	ds_read_b128 v[194:197], v152 offset:35840
	ds_read_b128 v[198:201], v152 offset:36864
	ds_read_b128 v[202:205], v152 offset:37888
	ds_read_b128 v[206:209], v152 offset:38912
	ds_read_b128 v[212:215], v152 offset:39936
	global_load_lds_dwordx4 v134, s[40:41]
	s_mov_b32 m0, s27
	s_nop 0
	global_load_lds_dwordx4 v130, s[40:41]
	s_waitcnt vmcnt(8)
	s_waitcnt lgkmcnt(0)
	s_barrier
	s_setprio 1
	v_mfma_f32_16x16x32_bf16 v[124:127], v[144:147], v[182:185], v[124:127]
	v_mfma_f32_16x16x32_bf16 v[120:123], v[158:161], v[182:185], v[120:123]
	v_mfma_f32_16x16x32_bf16 v[108:111], v[144:147], v[190:193], v[108:111]
	v_mfma_f32_16x16x32_bf16 v[104:107], v[158:161], v[190:193], v[104:107]
	v_mfma_f32_16x16x32_bf16 v[92:95], v[144:147], v[198:201], v[92:95]
	v_mfma_f32_16x16x32_bf16 v[88:91], v[158:161], v[198:201], v[88:91]
	v_mfma_f32_16x16x32_bf16 v[76:79], v[144:147], v[206:209], v[76:79]
	v_mfma_f32_16x16x32_bf16 v[72:75], v[158:161], v[206:209], v[72:75]
	v_mfma_f32_16x16x32_bf16 v[124:127], v[154:157], v[186:189], v[124:127]
	v_mfma_f32_16x16x32_bf16 v[120:123], v[162:165], v[186:189], v[120:123]
	v_mfma_f32_16x16x32_bf16 v[108:111], v[154:157], v[194:197], v[108:111]
	v_mfma_f32_16x16x32_bf16 v[104:107], v[162:165], v[194:197], v[104:107]
	v_mfma_f32_16x16x32_bf16 v[92:95], v[154:157], v[202:205], v[92:95]
	v_mfma_f32_16x16x32_bf16 v[88:91], v[162:165], v[202:205], v[88:91]
	v_mfma_f32_16x16x32_bf16 v[76:79], v[154:157], v[212:215], v[76:79]
	v_mfma_f32_16x16x32_bf16 v[72:75], v[162:165], v[212:215], v[72:75]
	s_setprio 0
	s_setprio 1
	v_mfma_f32_16x16x32_bf16 v[116:119], v[166:169], v[182:185], v[116:119]
	v_mfma_f32_16x16x32_bf16 v[112:115], v[174:177], v[182:185], v[112:115]
	v_mfma_f32_16x16x32_bf16 v[100:103], v[166:169], v[190:193], v[100:103]
	v_mfma_f32_16x16x32_bf16 v[96:99], v[174:177], v[190:193], v[96:99]
	v_mfma_f32_16x16x32_bf16 v[84:87], v[166:169], v[198:201], v[84:87]
	v_mfma_f32_16x16x32_bf16 v[80:83], v[174:177], v[198:201], v[80:83]
	v_mfma_f32_16x16x32_bf16 v[68:71], v[166:169], v[206:209], v[68:71]
	v_mfma_f32_16x16x32_bf16 v[64:67], v[174:177], v[206:209], v[64:67]
	v_mfma_f32_16x16x32_bf16 v[116:119], v[170:173], v[186:189], v[116:119]
	v_mfma_f32_16x16x32_bf16 v[112:115], v[178:181], v[186:189], v[112:115]
	v_mfma_f32_16x16x32_bf16 v[100:103], v[170:173], v[194:197], v[100:103]
	v_mfma_f32_16x16x32_bf16 v[96:99], v[178:181], v[194:197], v[96:99]
	v_mfma_f32_16x16x32_bf16 v[84:87], v[170:173], v[202:205], v[84:87]
	v_mfma_f32_16x16x32_bf16 v[80:83], v[178:181], v[202:205], v[80:83]
	v_mfma_f32_16x16x32_bf16 v[68:71], v[170:173], v[212:215], v[68:71]
	v_mfma_f32_16x16x32_bf16 v[64:67], v[178:181], v[212:215], v[64:67]
	s_setprio 0
	s_barrier
	s_mov_b32 m0, s58
	v_lshl_add_u64 v[216:217], v[216:217], 0, s[2:3]
	ds_read_b128 v[182:185], v152 offset:49152
	ds_read_b128 v[186:189], v152 offset:50176
	ds_read_b128 v[190:193], v152 offset:51200
	ds_read_b128 v[194:197], v152 offset:52224
	ds_read_b128 v[198:201], v152 offset:53248
	ds_read_b128 v[202:205], v152 offset:54272
	ds_read_b128 v[206:209], v152 offset:55296
	ds_read_b128 v[212:215], v152 offset:56320
	global_load_lds_dwordx4 v[216:217], off
	v_lshl_add_u64 v[216:217], v[218:219], 0, s[2:3]
	s_mov_b32 m0, s56
	s_nop 0
	global_load_lds_dwordx4 v[216:217], off
	s_mov_b32 m0, s57
	s_nop 0
	global_load_lds_dwordx4 v132, s[38:39]
	s_mov_b32 m0, s55
	s_nop 0
	global_load_lds_dwordx4 v128, s[38:39]
	v_lshl_add_u64 v[216:217], v[220:221], 0, s[2:3]
	s_mov_b32 m0, s29
	s_nop 0
	global_load_lds_dwordx4 v[216:217], off
	v_lshl_add_u64 v[216:217], v[222:223], 0, s[2:3]
	s_mov_b32 m0, s33
	s_nop 0
	global_load_lds_dwordx4 v[216:217], off
	s_waitcnt vmcnt(8)
	s_waitcnt lgkmcnt(0)
	s_barrier
	s_setprio 1
	v_mfma_f32_16x16x32_bf16 v[60:63], v[144:147], v[182:185], v[60:63]
	v_mfma_f32_16x16x32_bf16 v[56:59], v[158:161], v[182:185], v[56:59]
	v_mfma_f32_16x16x32_bf16 v[44:47], v[144:147], v[190:193], v[44:47]
	v_mfma_f32_16x16x32_bf16 v[40:43], v[158:161], v[190:193], v[40:43]
	v_mfma_f32_16x16x32_bf16 v[28:31], v[144:147], v[198:201], v[28:31]
	v_mfma_f32_16x16x32_bf16 v[24:27], v[158:161], v[198:201], v[24:27]
	v_mfma_f32_16x16x32_bf16 v[12:15], v[144:147], v[206:209], v[12:15]
	v_mfma_f32_16x16x32_bf16 v[8:11], v[158:161], v[206:209], v[8:11]
	v_mfma_f32_16x16x32_bf16 v[60:63], v[154:157], v[186:189], v[60:63]
	v_mfma_f32_16x16x32_bf16 v[56:59], v[162:165], v[186:189], v[56:59]
	v_mfma_f32_16x16x32_bf16 v[44:47], v[154:157], v[194:197], v[44:47]
	v_mfma_f32_16x16x32_bf16 v[40:43], v[162:165], v[194:197], v[40:43]
	v_mfma_f32_16x16x32_bf16 v[28:31], v[154:157], v[202:205], v[28:31]
	v_mfma_f32_16x16x32_bf16 v[24:27], v[162:165], v[202:205], v[24:27]
	v_mfma_f32_16x16x32_bf16 v[12:15], v[154:157], v[212:215], v[12:15]
	v_mfma_f32_16x16x32_bf16 v[8:11], v[162:165], v[212:215], v[8:11]
	s_setprio 0
	s_setprio 1
	v_mfma_f32_16x16x32_bf16 v[52:55], v[166:169], v[182:185], v[52:55]
	v_mfma_f32_16x16x32_bf16 v[48:51], v[174:177], v[182:185], v[48:51]
	v_mfma_f32_16x16x32_bf16 v[36:39], v[166:169], v[190:193], v[36:39]
	v_mfma_f32_16x16x32_bf16 v[32:35], v[174:177], v[190:193], v[32:35]
	v_mfma_f32_16x16x32_bf16 v[20:23], v[166:169], v[198:201], v[20:23]
	v_mfma_f32_16x16x32_bf16 v[16:19], v[174:177], v[198:201], v[16:19]
	v_mfma_f32_16x16x32_bf16 v[4:7], v[166:169], v[206:209], v[4:7]
	v_mfma_f32_16x16x32_bf16 v[0:3], v[174:177], v[206:209], v[0:3]
	v_mfma_f32_16x16x32_bf16 v[52:55], v[170:173], v[186:189], v[52:55]
	v_mfma_f32_16x16x32_bf16 v[48:51], v[178:181], v[186:189], v[48:51]
	v_mfma_f32_16x16x32_bf16 v[36:39], v[170:173], v[194:197], v[36:39]
	v_mfma_f32_16x16x32_bf16 v[32:35], v[178:181], v[194:197], v[32:35]
	v_mfma_f32_16x16x32_bf16 v[20:23], v[170:173], v[202:205], v[20:23]
	v_mfma_f32_16x16x32_bf16 v[16:19], v[178:181], v[202:205], v[16:19]
	v_mfma_f32_16x16x32_bf16 v[4:7], v[170:173], v[212:215], v[4:7]
	v_mfma_f32_16x16x32_bf16 v[0:3], v[178:181], v[212:215], v[0:3]
	s_setprio 0
	s_barrier
	s_andn2_b64 vcc, exec, s[36:37]
	s_mov_b64 s[38:39], -1
	s_mov_b64 s[36:37], 0
	s_mov_b64 s[40:41], 0x100
	s_cbranch_vccz .LBB0_894
	s_and_b64 vcc, exec, s[6:7]
	s_cbranch_vccz .LBB0_897
	s_barrier

.LBB0_1155:
	v_add_u32_e32 v1, s46, v193
	ds_read_b128 v[72:75], v1
	ds_read_b128 v[76:79], v1 offset:1024
	ds_read_b128 v[84:87], v1 offset:2048
	ds_read_b128 v[188:191], v1 offset:3072
	v_add_u32_e32 v1, s47, v193
	s_add_u32 s34, s28, s30
	ds_read_b128 v[198:201], v1
	ds_read_b128 v[202:205], v1 offset:1024
	ds_read_b128 v[206:209], v1 offset:2048
	ds_read_b128 v[210:213], v1 offset:3072
	s_addc_u32 s35, s29, s31
	s_add_u32 s34, s34, 0x100
	s_addc_u32 s35, s35, 0
	s_add_u32 s53, s50, s30
	s_addc_u32 s54, s51, s31
	s_cmpk_eq_i32 s30, 0x700
	s_cselect_b32 s37, s21, s35
	s_cselect_b32 s36, s27, s34
	s_cselect_b32 s35, s19, s54
	s_cselect_b32 s34, s49, s53
	v_lshl_add_u64 v[2:3], v[112:113], 0, s[30:31]
	s_add_i32 m0, s38, 0xc000
	ds_read_b128 v[216:219], v197
	ds_read_b128 v[220:223], v197 offset:1024
	ds_read_b128 v[224:227], v197 offset:2048
	ds_read_b128 v[228:231], v197 offset:3072
	ds_read_b128 v[232:235], v197 offset:4096
	ds_read_b128 v[236:239], v197 offset:5120
	ds_read_b128 v[240:243], v197 offset:6144
	ds_read_b128 v[244:247], v197 offset:7168
	global_load_lds_dwordx4 v[2:3], off
	v_lshl_add_u64 v[2:3], v[114:115], 0, s[30:31]
	s_add_i32 m0, s38, 0xe000
	s_nop 0
	global_load_lds_dwordx4 v[2:3], off
	s_waitcnt vmcnt(8)
	s_waitcnt lgkmcnt(0)
	s_barrier
	s_setprio 1
	v_mfma_f32_16x16x32_bf16 v[156:159], v[72:75], v[216:219], v[156:159]
	v_mfma_f32_16x16x32_bf16 v[160:163], v[84:87], v[216:219], v[160:163]
	v_mfma_f32_16x16x32_bf16 v[144:147], v[72:75], v[224:227], v[144:147]
	v_mfma_f32_16x16x32_bf16 v[140:143], v[84:87], v[224:227], v[140:143]
	v_mfma_f32_16x16x32_bf16 v[128:131], v[72:75], v[232:235], v[128:131]
	v_mfma_f32_16x16x32_bf16 v[124:127], v[84:87], v[232:235], v[124:127]
	v_mfma_f32_16x16x32_bf16 v[96:99], v[72:75], v[240:243], v[96:99]
	v_mfma_f32_16x16x32_bf16 v[92:95], v[84:87], v[240:243], v[92:95]
	v_mfma_f32_16x16x32_bf16 v[156:159], v[76:79], v[220:223], v[156:159]
	v_mfma_f32_16x16x32_bf16 v[160:163], v[188:191], v[220:223], v[160:163]
	v_mfma_f32_16x16x32_bf16 v[144:147], v[76:79], v[228:231], v[144:147]
	v_mfma_f32_16x16x32_bf16 v[140:143], v[188:191], v[228:231], v[140:143]
	v_mfma_f32_16x16x32_bf16 v[128:131], v[76:79], v[236:239], v[128:131]
	v_mfma_f32_16x16x32_bf16 v[124:127], v[188:191], v[236:239], v[124:127]
	v_mfma_f32_16x16x32_bf16 v[96:99], v[76:79], v[244:247], v[96:99]
	v_mfma_f32_16x16x32_bf16 v[92:95], v[188:191], v[244:247], v[92:95]
	s_setprio 0
	s_setprio 1
	v_mfma_f32_16x16x32_bf16 v[152:155], v[198:201], v[216:219], v[152:155]
	v_mfma_f32_16x16x32_bf16 v[148:151], v[206:209], v[216:219], v[148:151]
	v_mfma_f32_16x16x32_bf16 v[136:139], v[198:201], v[224:227], v[136:139]
	v_mfma_f32_16x16x32_bf16 v[132:135], v[206:209], v[224:227], v[132:135]
	v_mfma_f32_16x16x32_bf16 v[120:123], v[198:201], v[232:235], v[120:123]
	v_mfma_f32_16x16x32_bf16 v[116:119], v[206:209], v[232:235], v[116:119]
	v_mfma_f32_16x16x32_bf16 v[80:83], v[198:201], v[240:243], v[80:83]
	v_mfma_f32_16x16x32_bf16 v[68:71], v[206:209], v[240:243], v[68:71]
	v_mfma_f32_16x16x32_bf16 v[152:155], v[202:205], v[220:223], v[152:155]
	v_mfma_f32_16x16x32_bf16 v[148:151], v[210:213], v[220:223], v[148:151]
	v_mfma_f32_16x16x32_bf16 v[136:139], v[202:205], v[228:231], v[136:139]
	v_mfma_f32_16x16x32_bf16 v[132:135], v[210:213], v[228:231], v[132:135]
	v_mfma_f32_16x16x32_bf16 v[120:123], v[202:205], v[236:239], v[120:123]
	v_mfma_f32_16x16x32_bf16 v[116:119], v[210:213], v[236:239], v[116:119]
	v_mfma_f32_16x16x32_bf16 v[80:83], v[202:205], v[244:247], v[80:83]
	v_mfma_f32_16x16x32_bf16 v[68:71], v[210:213], v[244:247], v[68:71]
	s_setprio 0
	s_barrier
	s_add_i32 s53, s46, s33
	v_lshl_add_u64 v[248:249], s[34:35], 0, v[166:167]
	s_mov_b32 m0, s53
	ds_read_b128 v[216:219], v197 offset:16384
	ds_read_b128 v[220:223], v197 offset:17408
	ds_read_b128 v[224:227], v197 offset:18432
	ds_read_b128 v[228:231], v197 offset:19456
	ds_read_b128 v[232:235], v197 offset:20480
	ds_read_b128 v[236:239], v197 offset:21504
	ds_read_b128 v[240:243], v197 offset:22528
	ds_read_b128 v[244:247], v197 offset:23552
	global_load_lds_dwordx4 v[248:249], off
	s_add_i32 m0, s53, 0x2000
	s_add_u32 s54, s34, 0x40000
	v_lshl_add_u64 v[250:251], s[34:35], 0, v[170:171]
	s_addc_u32 s55, s35, 0
	s_add_i32 s53, s47, s33
	global_load_lds_dwordx4 v[250:251], off
	s_mov_b32 m0, s53
	v_lshl_add_u64 v[252:253], s[36:37], 0, v[164:165]
	global_load_lds_dwordx4 v166, s[54:55]
	s_add_i32 m0, s53, 0x2000
	v_lshl_add_u64 v[176:177], s[36:37], 0, v[168:169]
	global_load_lds_dwordx4 v170, s[54:55]
	s_mov_b32 m0, s38
	s_nop 0
	global_load_lds_dwordx4 v[252:253], off
	s_mov_b32 m0, s39
	s_nop 0
	global_load_lds_dwordx4 v[176:177], off
	s_waitcnt vmcnt(8)
	s_waitcnt lgkmcnt(0)
	s_barrier
	s_setprio 1
	v_mfma_f32_16x16x32_bf16 v[64:67], v[72:75], v[216:219], v[64:67]
	v_mfma_f32_16x16x32_bf16 v[60:63], v[84:87], v[216:219], v[60:63]
	v_mfma_f32_16x16x32_bf16 v[48:51], v[72:75], v[224:227], v[48:51]
	v_mfma_f32_16x16x32_bf16 v[44:47], v[84:87], v[224:227], v[44:47]
	v_mfma_f32_16x16x32_bf16 v[32:35], v[72:75], v[232:235], v[32:35]
	v_mfma_f32_16x16x32_bf16 v[28:31], v[84:87], v[232:235], v[28:31]
	v_mfma_f32_16x16x32_bf16 v[16:19], v[72:75], v[240:243], v[16:19]
	v_mfma_f32_16x16x32_bf16 v[12:15], v[84:87], v[240:243], v[12:15]
	v_mfma_f32_16x16x32_bf16 v[64:67], v[76:79], v[220:223], v[64:67]
	v_mfma_f32_16x16x32_bf16 v[60:63], v[188:191], v[220:223], v[60:63]
	v_mfma_f32_16x16x32_bf16 v[48:51], v[76:79], v[228:231], v[48:51]
	v_mfma_f32_16x16x32_bf16 v[44:47], v[188:191], v[228:231], v[44:47]
	v_mfma_f32_16x16x32_bf16 v[32:35], v[76:79], v[236:239], v[32:35]
	v_mfma_f32_16x16x32_bf16 v[28:31], v[188:191], v[236:239], v[28:31]
	v_mfma_f32_16x16x32_bf16 v[16:19], v[76:79], v[244:247], v[16:19]
	v_mfma_f32_16x16x32_bf16 v[12:15], v[188:191], v[244:247], v[12:15]
	s_setprio 0
	s_setprio 1
	v_mfma_f32_16x16x32_bf16 v[56:59], v[198:201], v[216:219], v[56:59]
	v_mfma_f32_16x16x32_bf16 v[52:55], v[206:209], v[216:219], v[52:55]
	v_mfma_f32_16x16x32_bf16 v[40:43], v[198:201], v[224:227], v[40:43]
	v_mfma_f32_16x16x32_bf16 v[36:39], v[206:209], v[224:227], v[36:39]
	v_mfma_f32_16x16x32_bf16 v[24:27], v[198:201], v[232:235], v[24:27]
	v_mfma_f32_16x16x32_bf16 v[20:23], v[206:209], v[232:235], v[20:23]
	v_mfma_f32_16x16x32_bf16 v[8:11], v[198:201], v[240:243], v[8:11]
	v_mfma_f32_16x16x32_bf16 v[2:5], v[206:209], v[240:243], v[4:7]
	v_mfma_f32_16x16x32_bf16 v[56:59], v[202:205], v[220:223], v[56:59]
	v_mfma_f32_16x16x32_bf16 v[52:55], v[210:213], v[220:223], v[52:55]
	v_mfma_f32_16x16x32_bf16 v[40:43], v[202:205], v[228:231], v[40:43]
	v_mfma_f32_16x16x32_bf16 v[36:39], v[210:213], v[228:231], v[36:39]
	v_mfma_f32_16x16x32_bf16 v[24:27], v[202:205], v[236:239], v[24:27]
	v_mfma_f32_16x16x32_bf16 v[20:23], v[210:213], v[236:239], v[20:23]
	v_mfma_f32_16x16x32_bf16 v[8:11], v[202:205], v[244:247], v[8:11]
	v_mfma_f32_16x16x32_bf16 v[2:5], v[210:213], v[244:247], v[2:5]
	s_setprio 0
	s_barrier
	s_add_i32 s53, 0, 0x18000
	v_add_u32_e32 v1, s53, v193
	s_add_i32 s54, 0, 0x1c000
	ds_read_b128 v[72:75], v1
	ds_read_b128 v[76:79], v1 offset:1024
	ds_read_b128 v[84:87], v1 offset:2048
	ds_read_b128 v[188:191], v1 offset:3072
	v_add_u32_e32 v1, s54, v193
	ds_read_b128 v[198:201], v1
	ds_read_b128 v[202:205], v1 offset:1024
	ds_read_b128 v[206:209], v1 offset:2048
	ds_read_b128 v[210:213], v1 offset:3072
	s_add_u32 s36, s36, 0x40000
	s_addc_u32 s37, s37, 0
	s_mov_b32 m0, s40
	ds_read_b128 v[216:219], v197 offset:32768
	ds_read_b128 v[220:223], v197 offset:33792
	ds_read_b128 v[224:227], v197 offset:34816
	ds_read_b128 v[228:231], v197 offset:35840
	ds_read_b128 v[232:235], v197 offset:36864
	ds_read_b128 v[236:239], v197 offset:37888
	ds_read_b128 v[240:243], v197 offset:38912
	ds_read_b128 v[244:247], v197 offset:39936
	global_load_lds_dwordx4 v164, s[36:37]
	s_mov_b32 m0, s41
	s_nop 0
	global_load_lds_dwordx4 v168, s[36:37]
	s_waitcnt vmcnt(8)
	s_waitcnt lgkmcnt(0)
	s_barrier
	s_setprio 1
	v_mfma_f32_16x16x32_bf16 v[156:159], v[72:75], v[216:219], v[156:159]
	v_mfma_f32_16x16x32_bf16 v[160:163], v[84:87], v[216:219], v[160:163]
	v_mfma_f32_16x16x32_bf16 v[144:147], v[72:75], v[224:227], v[144:147]
	v_mfma_f32_16x16x32_bf16 v[140:143], v[84:87], v[224:227], v[140:143]
	v_mfma_f32_16x16x32_bf16 v[128:131], v[72:75], v[232:235], v[128:131]
	v_mfma_f32_16x16x32_bf16 v[124:127], v[84:87], v[232:235], v[124:127]
	v_mfma_f32_16x16x32_bf16 v[96:99], v[72:75], v[240:243], v[96:99]
	v_mfma_f32_16x16x32_bf16 v[92:95], v[84:87], v[240:243], v[92:95]
	v_mfma_f32_16x16x32_bf16 v[156:159], v[76:79], v[220:223], v[156:159]
	v_mfma_f32_16x16x32_bf16 v[160:163], v[188:191], v[220:223], v[160:163]
	v_mfma_f32_16x16x32_bf16 v[144:147], v[76:79], v[228:231], v[144:147]
	v_mfma_f32_16x16x32_bf16 v[140:143], v[188:191], v[228:231], v[140:143]
	v_mfma_f32_16x16x32_bf16 v[128:131], v[76:79], v[236:239], v[128:131]
	v_mfma_f32_16x16x32_bf16 v[124:127], v[188:191], v[236:239], v[124:127]
	v_mfma_f32_16x16x32_bf16 v[96:99], v[76:79], v[244:247], v[96:99]
	v_mfma_f32_16x16x32_bf16 v[92:95], v[188:191], v[244:247], v[92:95]
	s_setprio 0
	s_setprio 1
	v_mfma_f32_16x16x32_bf16 v[152:155], v[198:201], v[216:219], v[152:155]
	v_mfma_f32_16x16x32_bf16 v[148:151], v[206:209], v[216:219], v[148:151]
	v_mfma_f32_16x16x32_bf16 v[136:139], v[198:201], v[224:227], v[136:139]
	v_mfma_f32_16x16x32_bf16 v[132:135], v[206:209], v[224:227], v[132:135]
	v_mfma_f32_16x16x32_bf16 v[120:123], v[198:201], v[232:235], v[120:123]
	v_mfma_f32_16x16x32_bf16 v[116:119], v[206:209], v[232:235], v[116:119]
	v_mfma_f32_16x16x32_bf16 v[80:83], v[198:201], v[240:243], v[80:83]
	v_mfma_f32_16x16x32_bf16 v[68:71], v[206:209], v[240:243], v[68:71]
	v_mfma_f32_16x16x32_bf16 v[152:155], v[202:205], v[220:223], v[152:155]
	v_mfma_f32_16x16x32_bf16 v[148:151], v[210:213], v[220:223], v[148:151]
	v_mfma_f32_16x16x32_bf16 v[136:139], v[202:205], v[228:231], v[136:139]
	v_mfma_f32_16x16x32_bf16 v[132:135], v[210:213], v[228:231], v[132:135]
	v_mfma_f32_16x16x32_bf16 v[120:123], v[202:205], v[236:239], v[120:123]
	v_mfma_f32_16x16x32_bf16 v[116:119], v[210:213], v[236:239], v[116:119]
	v_mfma_f32_16x16x32_bf16 v[80:83], v[202:205], v[244:247], v[80:83]
	v_mfma_f32_16x16x32_bf16 v[68:71], v[210:213], v[244:247], v[68:71]
	s_setprio 0
	s_barrier
	s_add_i32 s36, s53, s33
	v_lshl_add_u64 v[6:7], v[248:249], 0, s[10:11]
	s_mov_b32 m0, s36
	ds_read_b128 v[216:219], v197 offset:49152
	ds_read_b128 v[220:223], v197 offset:50176
	ds_read_b128 v[224:227], v197 offset:51200
	ds_read_b128 v[228:231], v197 offset:52224
	ds_read_b128 v[232:235], v197 offset:53248
	ds_read_b128 v[236:239], v197 offset:54272
	ds_read_b128 v[240:243], v197 offset:55296
	ds_read_b128 v[244:247], v197 offset:56320
	global_load_lds_dwordx4 v[6:7], off
	s_add_i32 m0, s36, 0x2000
	s_add_u32 s34, s34, 0x40080
	v_lshl_add_u64 v[6:7], v[250:251], 0, s[10:11]
	s_addc_u32 s35, s35, 0
	s_add_i32 s36, s54, s33
	global_load_lds_dwordx4 v[6:7], off
	s_mov_b32 m0, s36
	s_nop 0
	global_load_lds_dwordx4 v166, s[34:35]
	s_add_i32 m0, s36, 0x2000
	s_nop 0
	global_load_lds_dwordx4 v170, s[34:35]
	v_lshl_add_u64 v[6:7], v[252:253], 0, s[10:11]
	s_mov_b32 m0, s43
	s_nop 0
	global_load_lds_dwordx4 v[6:7], off
	v_lshl_add_u64 v[6:7], v[176:177], 0, s[10:11]
	s_mov_b32 m0, s44
	s_nop 0
	global_load_lds_dwordx4 v[6:7], off
	s_waitcnt vmcnt(8)
	s_waitcnt lgkmcnt(0)
	s_barrier
	s_setprio 1
	v_mfma_f32_16x16x32_bf16 v[64:67], v[72:75], v[216:219], v[64:67]
	v_mfma_f32_16x16x32_bf16 v[60:63], v[84:87], v[216:219], v[60:63]
	v_mfma_f32_16x16x32_bf16 v[48:51], v[72:75], v[224:227], v[48:51]
	v_mfma_f32_16x16x32_bf16 v[44:47], v[84:87], v[224:227], v[44:47]
	v_mfma_f32_16x16x32_bf16 v[32:35], v[72:75], v[232:235], v[32:35]
	v_mfma_f32_16x16x32_bf16 v[28:31], v[84:87], v[232:235], v[28:31]
	v_mfma_f32_16x16x32_bf16 v[16:19], v[72:75], v[240:243], v[16:19]
	v_mfma_f32_16x16x32_bf16 v[12:15], v[84:87], v[240:243], v[12:15]
	v_mfma_f32_16x16x32_bf16 v[64:67], v[76:79], v[220:223], v[64:67]
	v_mfma_f32_16x16x32_bf16 v[60:63], v[188:191], v[220:223], v[60:63]
	v_mfma_f32_16x16x32_bf16 v[48:51], v[76:79], v[228:231], v[48:51]
	v_mfma_f32_16x16x32_bf16 v[44:47], v[188:191], v[228:231], v[44:47]
	v_mfma_f32_16x16x32_bf16 v[32:35], v[76:79], v[236:239], v[32:35]
	v_mfma_f32_16x16x32_bf16 v[28:31], v[188:191], v[236:239], v[28:31]
	v_mfma_f32_16x16x32_bf16 v[16:19], v[76:79], v[244:247], v[16:19]
	v_mfma_f32_16x16x32_bf16 v[12:15], v[188:191], v[244:247], v[12:15]
	s_setprio 0
	s_setprio 1
	v_mfma_f32_16x16x32_bf16 v[56:59], v[198:201], v[216:219], v[56:59]
	v_mfma_f32_16x16x32_bf16 v[52:55], v[206:209], v[216:219], v[52:55]
	v_mfma_f32_16x16x32_bf16 v[40:43], v[198:201], v[224:227], v[40:43]
	v_mfma_f32_16x16x32_bf16 v[36:39], v[206:209], v[224:227], v[36:39]
	v_mfma_f32_16x16x32_bf16 v[24:27], v[198:201], v[232:235], v[24:27]
	v_mfma_f32_16x16x32_bf16 v[20:23], v[206:209], v[232:235], v[20:23]
	v_mfma_f32_16x16x32_bf16 v[6:9], v[198:201], v[240:243], v[8:11]
	v_mfma_f32_16x16x32_bf16 v[2:5], v[206:209], v[240:243], v[2:5]
	v_mfma_f32_16x16x32_bf16 v[56:59], v[202:205], v[220:223], v[56:59]
	v_mfma_f32_16x16x32_bf16 v[52:55], v[210:213], v[220:223], v[52:55]
	v_mfma_f32_16x16x32_bf16 v[40:43], v[202:205], v[228:231], v[40:43]
	v_mfma_f32_16x16x32_bf16 v[36:39], v[210:213], v[228:231], v[36:39]
	v_mfma_f32_16x16x32_bf16 v[24:27], v[202:205], v[236:239], v[24:27]
	v_mfma_f32_16x16x32_bf16 v[20:23], v[210:213], v[236:239], v[20:23]
	v_mfma_f32_16x16x32_bf16 v[8:11], v[202:205], v[244:247], v[6:9]
	v_mfma_f32_16x16x32_bf16 v[4:7], v[210:213], v[244:247], v[2:5]
	s_setprio 0
	s_barrier
	s_add_i32 s52, s52, 2
	s_add_u32 s30, s30, 0x100
	s_addc_u32 s31, s31, 0
	s_cmp_gt_u32 s52, 13
	s_cbranch_scc1 .LBB0_1158

.LBB0_1243:
	ds_read_b128 v[128:131], v183
	ds_read_b128 v[132:135], v183 offset:1024
	ds_read_b128 v[136:139], v183 offset:2048
	ds_read_b128 v[140:143], v183 offset:3072
	ds_read_b128 v[144:147], v184
	ds_read_b128 v[164:167], v184 offset:1024
	ds_read_b128 v[168:171], v184 offset:2048
	ds_read_b128 v[172:175], v184 offset:3072
	s_add_u32 s20, s18, 0xfffc0080
	s_addc_u32 s21, s19, -1
	s_cmp_eq_u32 s44, 12
	s_cselect_b32 s23, s13, s21
	s_cselect_b32 s22, s40, s20
	s_cselect_b32 s21, s11, s43
	s_cselect_b32 s20, s41, s42
	s_add_i32 m0, s25, 0xc000
	ds_read_b128 v[176:179], v185
	ds_read_b128 v[188:191], v185 offset:1024
	ds_read_b128 v[192:195], v185 offset:2048
	ds_read_b128 v[196:199], v185 offset:3072
	ds_read_b128 v[200:203], v185 offset:4096
	ds_read_b128 v[204:207], v185 offset:5120
	ds_read_b128 v[208:211], v185 offset:6144
	ds_read_b128 v[216:219], v185 offset:7168
	global_load_lds_dwordx4 v156, s[18:19]
	s_add_i32 m0, s25, 0xe000
	s_nop 0
	global_load_lds_dwordx4 v158, s[18:19]
	s_waitcnt vmcnt(8)
	s_waitcnt lgkmcnt(0)
	s_barrier
	s_setprio 1
	v_mfma_f32_16x16x32_bf16 v[124:127], v[128:131], v[176:179], v[124:127]
	v_mfma_f32_16x16x32_bf16 v[120:123], v[136:139], v[176:179], v[120:123]
	v_mfma_f32_16x16x32_bf16 v[116:119], v[128:131], v[192:195], v[116:119]
	v_mfma_f32_16x16x32_bf16 v[112:115], v[136:139], v[192:195], v[112:115]
	v_mfma_f32_16x16x32_bf16 v[108:111], v[128:131], v[200:203], v[108:111]
	v_mfma_f32_16x16x32_bf16 v[100:103], v[136:139], v[200:203], v[100:103]
	v_mfma_f32_16x16x32_bf16 v[88:91], v[128:131], v[208:211], v[88:91]
	v_mfma_f32_16x16x32_bf16 v[80:83], v[136:139], v[208:211], v[80:83]
	v_mfma_f32_16x16x32_bf16 v[124:127], v[132:135], v[188:191], v[124:127]
	v_mfma_f32_16x16x32_bf16 v[120:123], v[140:143], v[188:191], v[120:123]
	v_mfma_f32_16x16x32_bf16 v[116:119], v[132:135], v[196:199], v[116:119]
	v_mfma_f32_16x16x32_bf16 v[112:115], v[140:143], v[196:199], v[112:115]
	v_mfma_f32_16x16x32_bf16 v[108:111], v[132:135], v[204:207], v[108:111]
	v_mfma_f32_16x16x32_bf16 v[100:103], v[140:143], v[204:207], v[100:103]
	v_mfma_f32_16x16x32_bf16 v[88:91], v[132:135], v[216:219], v[88:91]
	v_mfma_f32_16x16x32_bf16 v[80:83], v[140:143], v[216:219], v[80:83]
	s_setprio 0
	s_setprio 1
	v_mfma_f32_16x16x32_bf16 v[104:107], v[144:147], v[176:179], v[104:107]
	v_mfma_f32_16x16x32_bf16 v[96:99], v[168:171], v[176:179], v[96:99]
	v_mfma_f32_16x16x32_bf16 v[92:95], v[144:147], v[192:195], v[92:95]
	v_mfma_f32_16x16x32_bf16 v[84:87], v[168:171], v[192:195], v[84:87]
	v_mfma_f32_16x16x32_bf16 v[76:79], v[144:147], v[200:203], v[76:79]
	v_mfma_f32_16x16x32_bf16 v[72:75], v[168:171], v[200:203], v[72:75]
	v_mfma_f32_16x16x32_bf16 v[68:71], v[144:147], v[208:211], v[68:71]
	v_mfma_f32_16x16x32_bf16 v[64:67], v[168:171], v[208:211], v[64:67]
	v_mfma_f32_16x16x32_bf16 v[104:107], v[164:167], v[188:191], v[104:107]
	v_mfma_f32_16x16x32_bf16 v[96:99], v[172:175], v[188:191], v[96:99]
	v_mfma_f32_16x16x32_bf16 v[92:95], v[164:167], v[196:199], v[92:95]
	v_mfma_f32_16x16x32_bf16 v[84:87], v[172:175], v[196:199], v[84:87]
	v_mfma_f32_16x16x32_bf16 v[76:79], v[164:167], v[204:207], v[76:79]
	v_mfma_f32_16x16x32_bf16 v[72:75], v[172:175], v[204:207], v[72:75]
	v_mfma_f32_16x16x32_bf16 v[68:71], v[164:167], v[216:219], v[68:71]
	v_mfma_f32_16x16x32_bf16 v[64:67], v[172:175], v[216:219], v[64:67]
	s_setprio 0
	s_barrier
	s_add_i32 s45, s36, s24
	v_lshl_add_u64 v[212:213], s[20:21], 0, v[152:153]
	s_mov_b32 m0, s45
	ds_read_b128 v[176:179], v185 offset:16384
	ds_read_b128 v[188:191], v185 offset:17408
	ds_read_b128 v[192:195], v185 offset:18432
	ds_read_b128 v[196:199], v185 offset:19456
	ds_read_b128 v[200:203], v185 offset:20480
	ds_read_b128 v[204:207], v185 offset:21504
	ds_read_b128 v[208:211], v185 offset:22528
	ds_read_b128 v[216:219], v185 offset:23552
	global_load_lds_dwordx4 v[212:213], off
	s_add_i32 m0, s45, 0x2000
	s_add_u32 s46, s20, 0x40000
	v_lshl_add_u64 v[220:221], s[20:21], 0, v[148:149]
	s_addc_u32 s47, s21, 0
	s_add_i32 s45, s37, s24
	global_load_lds_dwordx4 v[220:221], off
	s_mov_b32 m0, s45
	v_lshl_add_u64 v[224:225], s[22:23], 0, v[150:151]
	global_load_lds_dwordx4 v152, s[46:47]
	s_add_i32 m0, s45, 0x2000
	s_nop 0
	global_load_lds_dwordx4 v148, s[46:47]
	v_lshl_add_u64 v[222:223], s[22:23], 0, v[154:155]
	s_mov_b32 m0, s25
	s_nop 0
	global_load_lds_dwordx4 v[222:223], off
	s_mov_b32 m0, s26
	s_nop 0
	global_load_lds_dwordx4 v[224:225], off
	s_waitcnt vmcnt(8)
	s_waitcnt lgkmcnt(0)
	s_barrier
	s_setprio 1
	v_mfma_f32_16x16x32_bf16 v[60:63], v[128:131], v[176:179], v[60:63]
	v_mfma_f32_16x16x32_bf16 v[56:59], v[136:139], v[176:179], v[56:59]
	v_mfma_f32_16x16x32_bf16 v[52:55], v[128:131], v[192:195], v[52:55]
	v_mfma_f32_16x16x32_bf16 v[48:51], v[136:139], v[192:195], v[48:51]
	v_mfma_f32_16x16x32_bf16 v[40:43], v[128:131], v[200:203], v[40:43]
	v_mfma_f32_16x16x32_bf16 v[32:35], v[136:139], v[200:203], v[32:35]
	v_mfma_f32_16x16x32_bf16 v[20:23], v[128:131], v[208:211], v[20:23]
	v_mfma_f32_16x16x32_bf16 v[16:19], v[136:139], v[208:211], v[16:19]
	v_mfma_f32_16x16x32_bf16 v[60:63], v[132:135], v[188:191], v[60:63]
	v_mfma_f32_16x16x32_bf16 v[56:59], v[140:143], v[188:191], v[56:59]
	v_mfma_f32_16x16x32_bf16 v[52:55], v[132:135], v[196:199], v[52:55]
	v_mfma_f32_16x16x32_bf16 v[48:51], v[140:143], v[196:199], v[48:51]
	v_mfma_f32_16x16x32_bf16 v[40:43], v[132:135], v[204:207], v[40:43]
	v_mfma_f32_16x16x32_bf16 v[32:35], v[140:143], v[204:207], v[32:35]
	v_mfma_f32_16x16x32_bf16 v[20:23], v[132:135], v[216:219], v[20:23]
	v_mfma_f32_16x16x32_bf16 v[16:19], v[140:143], v[216:219], v[16:19]
	s_setprio 0
	s_setprio 1
	v_mfma_f32_16x16x32_bf16 v[44:47], v[144:147], v[176:179], v[44:47]
	v_mfma_f32_16x16x32_bf16 v[36:39], v[168:171], v[176:179], v[36:39]
	v_mfma_f32_16x16x32_bf16 v[28:31], v[144:147], v[192:195], v[28:31]
	v_mfma_f32_16x16x32_bf16 v[24:27], v[168:171], v[192:195], v[24:27]
	v_mfma_f32_16x16x32_bf16 v[12:15], v[144:147], v[200:203], v[12:15]
	v_mfma_f32_16x16x32_bf16 v[8:11], v[168:171], v[200:203], v[8:11]
	v_mfma_f32_16x16x32_bf16 v[4:7], v[144:147], v[208:211], v[4:7]
	v_mfma_f32_16x16x32_bf16 v[0:3], v[168:171], v[208:211], v[0:3]
	v_mfma_f32_16x16x32_bf16 v[44:47], v[164:167], v[188:191], v[44:47]
	v_mfma_f32_16x16x32_bf16 v[36:39], v[172:175], v[188:191], v[36:39]
	v_mfma_f32_16x16x32_bf16 v[28:31], v[164:167], v[196:199], v[28:31]
	v_mfma_f32_16x16x32_bf16 v[24:27], v[172:175], v[196:199], v[24:27]
	v_mfma_f32_16x16x32_bf16 v[12:15], v[164:167], v[204:207], v[12:15]
	v_mfma_f32_16x16x32_bf16 v[8:11], v[172:175], v[204:207], v[8:11]
	v_mfma_f32_16x16x32_bf16 v[4:7], v[164:167], v[216:219], v[4:7]
	v_mfma_f32_16x16x32_bf16 v[0:3], v[172:175], v[216:219], v[0:3]
	s_setprio 0
	s_barrier
	s_add_i32 s45, 0, 0x18000
	s_add_i32 s46, 0, 0x1c000
	v_add_u32_e32 v140, s45, v181
	v_add_u32_e32 v172, s46, v181
	ds_read_b128 v[128:131], v140
	ds_read_b128 v[132:135], v140 offset:1024
	ds_read_b128 v[136:139], v140 offset:2048
	ds_read_b128 v[140:143], v140 offset:3072
	ds_read_b128 v[144:147], v172
	ds_read_b128 v[164:167], v172 offset:1024
	ds_read_b128 v[168:171], v172 offset:2048
	ds_read_b128 v[172:175], v172 offset:3072
	s_add_u32 s22, s22, 0x40000
	s_addc_u32 s23, s23, 0
	s_mov_b32 m0, s27
	ds_read_b128 v[176:179], v185 offset:32768
	ds_read_b128 v[188:191], v185 offset:33792
	ds_read_b128 v[192:195], v185 offset:34816
	ds_read_b128 v[196:199], v185 offset:35840
	ds_read_b128 v[200:203], v185 offset:36864
	ds_read_b128 v[204:207], v185 offset:37888
	ds_read_b128 v[208:211], v185 offset:38912
	ds_read_b128 v[216:219], v185 offset:39936
	global_load_lds_dwordx4 v154, s[22:23]
	s_mov_b32 m0, s28
	s_nop 0
	global_load_lds_dwordx4 v150, s[22:23]
	s_waitcnt vmcnt(8)
	s_waitcnt lgkmcnt(0)
	s_barrier
	s_setprio 1
	v_mfma_f32_16x16x32_bf16 v[124:127], v[128:131], v[176:179], v[124:127]
	v_mfma_f32_16x16x32_bf16 v[120:123], v[136:139], v[176:179], v[120:123]
	v_mfma_f32_16x16x32_bf16 v[116:119], v[128:131], v[192:195], v[116:119]
	v_mfma_f32_16x16x32_bf16 v[112:115], v[136:139], v[192:195], v[112:115]
	v_mfma_f32_16x16x32_bf16 v[108:111], v[128:131], v[200:203], v[108:111]
	v_mfma_f32_16x16x32_bf16 v[100:103], v[136:139], v[200:203], v[100:103]
	v_mfma_f32_16x16x32_bf16 v[88:91], v[128:131], v[208:211], v[88:91]
	v_mfma_f32_16x16x32_bf16 v[80:83], v[136:139], v[208:211], v[80:83]
	v_mfma_f32_16x16x32_bf16 v[124:127], v[132:135], v[188:191], v[124:127]
	v_mfma_f32_16x16x32_bf16 v[120:123], v[140:143], v[188:191], v[120:123]
	v_mfma_f32_16x16x32_bf16 v[116:119], v[132:135], v[196:199], v[116:119]
	v_mfma_f32_16x16x32_bf16 v[112:115], v[140:143], v[196:199], v[112:115]
	v_mfma_f32_16x16x32_bf16 v[108:111], v[132:135], v[204:207], v[108:111]
	v_mfma_f32_16x16x32_bf16 v[100:103], v[140:143], v[204:207], v[100:103]
	v_mfma_f32_16x16x32_bf16 v[88:91], v[132:135], v[216:219], v[88:91]
	v_mfma_f32_16x16x32_bf16 v[80:83], v[140:143], v[216:219], v[80:83]
	s_setprio 0
	s_setprio 1
	v_mfma_f32_16x16x32_bf16 v[104:107], v[144:147], v[176:179], v[104:107]
	v_mfma_f32_16x16x32_bf16 v[96:99], v[168:171], v[176:179], v[96:99]
	v_mfma_f32_16x16x32_bf16 v[92:95], v[144:147], v[192:195], v[92:95]
	v_mfma_f32_16x16x32_bf16 v[84:87], v[168:171], v[192:195], v[84:87]
	v_mfma_f32_16x16x32_bf16 v[76:79], v[144:147], v[200:203], v[76:79]
	v_mfma_f32_16x16x32_bf16 v[72:75], v[168:171], v[200:203], v[72:75]
	v_mfma_f32_16x16x32_bf16 v[68:71], v[144:147], v[208:211], v[68:71]
	v_mfma_f32_16x16x32_bf16 v[64:67], v[168:171], v[208:211], v[64:67]
	v_mfma_f32_16x16x32_bf16 v[104:107], v[164:167], v[188:191], v[104:107]
	v_mfma_f32_16x16x32_bf16 v[96:99], v[172:175], v[188:191], v[96:99]
	v_mfma_f32_16x16x32_bf16 v[92:95], v[164:167], v[196:199], v[92:95]
	v_mfma_f32_16x16x32_bf16 v[84:87], v[172:175], v[196:199], v[84:87]
	v_mfma_f32_16x16x32_bf16 v[76:79], v[164:167], v[204:207], v[76:79]
	v_mfma_f32_16x16x32_bf16 v[72:75], v[172:175], v[204:207], v[72:75]
	v_mfma_f32_16x16x32_bf16 v[68:71], v[164:167], v[216:219], v[68:71]
	v_mfma_f32_16x16x32_bf16 v[64:67], v[172:175], v[216:219], v[64:67]
	s_setprio 0
	s_barrier
	s_add_i32 s22, s45, s24
	v_lshl_add_u64 v[212:213], v[212:213], 0, s[6:7]
	s_mov_b32 m0, s22
	ds_read_b128 v[176:179], v185 offset:49152
	ds_read_b128 v[188:191], v185 offset:50176
	ds_read_b128 v[192:195], v185 offset:51200
	ds_read_b128 v[196:199], v185 offset:52224
	ds_read_b128 v[200:203], v185 offset:53248
	ds_read_b128 v[204:207], v185 offset:54272
	ds_read_b128 v[208:211], v185 offset:55296
	ds_read_b128 v[216:219], v185 offset:56320
	global_load_lds_dwordx4 v[212:213], off
	s_add_i32 m0, s22, 0x2000
	s_add_u32 s20, s20, 0x40080
	v_lshl_add_u64 v[212:213], v[220:221], 0, s[6:7]
	s_addc_u32 s21, s21, 0
	s_add_i32 s22, s46, s24
	global_load_lds_dwordx4 v[212:213], off
	s_mov_b32 m0, s22
	s_nop 0
	global_load_lds_dwordx4 v152, s[20:21]
	s_add_i32 m0, s22, 0x2000
	s_nop 0
	global_load_lds_dwordx4 v148, s[20:21]
	v_lshl_add_u64 v[212:213], v[222:223], 0, s[6:7]
	s_mov_b32 m0, s33
	s_nop 0
	global_load_lds_dwordx4 v[212:213], off
	v_lshl_add_u64 v[212:213], v[224:225], 0, s[6:7]
	s_mov_b32 m0, s34
	s_nop 0
	global_load_lds_dwordx4 v[212:213], off
	s_waitcnt vmcnt(8)
	s_waitcnt lgkmcnt(0)
	s_barrier
	s_setprio 1
	v_mfma_f32_16x16x32_bf16 v[60:63], v[128:131], v[176:179], v[60:63]
	v_mfma_f32_16x16x32_bf16 v[56:59], v[136:139], v[176:179], v[56:59]
	v_mfma_f32_16x16x32_bf16 v[52:55], v[128:131], v[192:195], v[52:55]
	v_mfma_f32_16x16x32_bf16 v[48:51], v[136:139], v[192:195], v[48:51]
	v_mfma_f32_16x16x32_bf16 v[40:43], v[128:131], v[200:203], v[40:43]
	v_mfma_f32_16x16x32_bf16 v[32:35], v[136:139], v[200:203], v[32:35]
	v_mfma_f32_16x16x32_bf16 v[20:23], v[128:131], v[208:211], v[20:23]
	v_mfma_f32_16x16x32_bf16 v[16:19], v[136:139], v[208:211], v[16:19]
	v_mfma_f32_16x16x32_bf16 v[60:63], v[132:135], v[188:191], v[60:63]
	v_mfma_f32_16x16x32_bf16 v[56:59], v[140:143], v[188:191], v[56:59]
	v_mfma_f32_16x16x32_bf16 v[52:55], v[132:135], v[196:199], v[52:55]
	v_mfma_f32_16x16x32_bf16 v[48:51], v[140:143], v[196:199], v[48:51]
	v_mfma_f32_16x16x32_bf16 v[40:43], v[132:135], v[204:207], v[40:43]
	v_mfma_f32_16x16x32_bf16 v[32:35], v[140:143], v[204:207], v[32:35]
	v_mfma_f32_16x16x32_bf16 v[20:23], v[132:135], v[216:219], v[20:23]
	v_mfma_f32_16x16x32_bf16 v[16:19], v[140:143], v[216:219], v[16:19]
	s_setprio 0
	s_setprio 1
	v_mfma_f32_16x16x32_bf16 v[44:47], v[144:147], v[176:179], v[44:47]
	v_mfma_f32_16x16x32_bf16 v[36:39], v[168:171], v[176:179], v[36:39]
	v_mfma_f32_16x16x32_bf16 v[28:31], v[144:147], v[192:195], v[28:31]
	v_mfma_f32_16x16x32_bf16 v[24:27], v[168:171], v[192:195], v[24:27]
	v_mfma_f32_16x16x32_bf16 v[12:15], v[144:147], v[200:203], v[12:15]
	v_mfma_f32_16x16x32_bf16 v[8:11], v[168:171], v[200:203], v[8:11]
	v_mfma_f32_16x16x32_bf16 v[4:7], v[144:147], v[208:211], v[4:7]
	v_mfma_f32_16x16x32_bf16 v[0:3], v[168:171], v[208:211], v[0:3]
	v_mfma_f32_16x16x32_bf16 v[44:47], v[164:167], v[188:191], v[44:47]
	v_mfma_f32_16x16x32_bf16 v[36:39], v[172:175], v[188:191], v[36:39]
	v_mfma_f32_16x16x32_bf16 v[28:31], v[164:167], v[196:199], v[28:31]
	v_mfma_f32_16x16x32_bf16 v[24:27], v[172:175], v[196:199], v[24:27]
	v_mfma_f32_16x16x32_bf16 v[12:15], v[164:167], v[204:207], v[12:15]
	v_mfma_f32_16x16x32_bf16 v[8:11], v[172:175], v[204:207], v[8:11]
	v_mfma_f32_16x16x32_bf16 v[4:7], v[164:167], v[216:219], v[4:7]
	v_mfma_f32_16x16x32_bf16 v[0:3], v[172:175], v[216:219], v[0:3]
	s_setprio 0
	s_barrier
	s_add_i32 s44, s44, 2
	s_add_u32 s18, s18, 0x100
	s_addc_u32 s19, s19, 0
	s_add_u32 s42, s42, 0x100
	s_addc_u32 s43, s43, 0
	s_cmp_gt_u32 s44, 13
	s_cbranch_scc0 .LBB0_1243
	s_and_b64 vcc, exec, s[8:9]
	s_cbranch_vccz .LBB0_1246
	s_barrier

.LBB0_1325:
	ds_read_b128 v[120:123], v209
	ds_read_b128 v[128:131], v209 offset:1024
	ds_read_b128 v[136:139], v209 offset:2048
	ds_read_b128 v[140:143], v209 offset:3072
	ds_read_b128 v[144:147], v210
	ds_read_b128 v[148:151], v210 offset:1024
	ds_read_b128 v[152:155], v210 offset:2048
	ds_read_b128 v[156:159], v210 offset:3072
	s_add_u32 s4, s22, 0x100
	s_addc_u32 s5, s23, 0
	s_cmp_eq_u32 s47, 40
	s_cselect_b32 s27, s17, s5
	s_cselect_b32 s26, s16, s4
	s_cselect_b32 s25, s19, s46
	s_cselect_b32 s24, s18, s21
	s_add_i32 m0, s29, 0xc000
	ds_read_b128 v[160:163], v211
	ds_read_b128 v[164:167], v211 offset:1024
	ds_read_b128 v[184:187], v211 offset:2048
	ds_read_b128 v[188:191], v211 offset:3072
	ds_read_b128 v[192:195], v211 offset:4096
	ds_read_b128 v[196:199], v211 offset:5120
	ds_read_b128 v[200:203], v211 offset:6144
	ds_read_b128 v[216:219], v211 offset:7168
	global_load_lds_dwordx4 v176, s[22:23]
	s_add_i32 m0, s29, 0xe000
	s_nop 0
	global_load_lds_dwordx4 v178, s[22:23]
	s_waitcnt vmcnt(8)
	s_waitcnt lgkmcnt(0)
	s_barrier
	s_setprio 1
	v_mfma_f32_16x16x32_bf16 v[132:135], v[120:123], v[160:163], v[132:135]
	v_mfma_f32_16x16x32_bf16 v[124:127], v[136:139], v[160:163], v[124:127]
	v_mfma_f32_16x16x32_bf16 v[108:111], v[120:123], v[184:187], v[108:111]
	v_mfma_f32_16x16x32_bf16 v[104:107], v[136:139], v[184:187], v[104:107]
	v_mfma_f32_16x16x32_bf16 v[92:95], v[120:123], v[192:195], v[92:95]
	v_mfma_f32_16x16x32_bf16 v[88:91], v[136:139], v[192:195], v[88:91]
	v_mfma_f32_16x16x32_bf16 v[76:79], v[120:123], v[200:203], v[76:79]
	v_mfma_f32_16x16x32_bf16 v[72:75], v[136:139], v[200:203], v[72:75]
	v_mfma_f32_16x16x32_bf16 v[132:135], v[128:131], v[164:167], v[132:135]
	v_mfma_f32_16x16x32_bf16 v[124:127], v[140:143], v[164:167], v[124:127]
	v_mfma_f32_16x16x32_bf16 v[108:111], v[128:131], v[188:191], v[108:111]
	v_mfma_f32_16x16x32_bf16 v[104:107], v[140:143], v[188:191], v[104:107]
	v_mfma_f32_16x16x32_bf16 v[92:95], v[128:131], v[196:199], v[92:95]
	v_mfma_f32_16x16x32_bf16 v[88:91], v[140:143], v[196:199], v[88:91]
	v_mfma_f32_16x16x32_bf16 v[76:79], v[128:131], v[216:219], v[76:79]
	v_mfma_f32_16x16x32_bf16 v[72:75], v[140:143], v[216:219], v[72:75]
	s_setprio 0
	s_setprio 1
	v_mfma_f32_16x16x32_bf16 v[116:119], v[144:147], v[160:163], v[116:119]
	v_mfma_f32_16x16x32_bf16 v[112:115], v[152:155], v[160:163], v[112:115]
	v_mfma_f32_16x16x32_bf16 v[100:103], v[144:147], v[184:187], v[100:103]
	v_mfma_f32_16x16x32_bf16 v[96:99], v[152:155], v[184:187], v[96:99]
	v_mfma_f32_16x16x32_bf16 v[84:87], v[144:147], v[192:195], v[84:87]
	v_mfma_f32_16x16x32_bf16 v[80:83], v[152:155], v[192:195], v[80:83]
	v_mfma_f32_16x16x32_bf16 v[68:71], v[144:147], v[200:203], v[68:71]
	v_mfma_f32_16x16x32_bf16 v[64:67], v[152:155], v[200:203], v[64:67]
	v_mfma_f32_16x16x32_bf16 v[116:119], v[148:151], v[164:167], v[116:119]
	v_mfma_f32_16x16x32_bf16 v[112:115], v[156:159], v[164:167], v[112:115]
	v_mfma_f32_16x16x32_bf16 v[100:103], v[148:151], v[188:191], v[100:103]
	v_mfma_f32_16x16x32_bf16 v[96:99], v[156:159], v[188:191], v[96:99]
	v_mfma_f32_16x16x32_bf16 v[84:87], v[148:151], v[196:199], v[84:87]
	v_mfma_f32_16x16x32_bf16 v[80:83], v[156:159], v[196:199], v[80:83]
	v_mfma_f32_16x16x32_bf16 v[68:71], v[148:151], v[216:219], v[68:71]
	v_mfma_f32_16x16x32_bf16 v[64:67], v[156:159], v[216:219], v[64:67]
	s_setprio 0
	s_barrier
	s_add_i32 s22, s41, s28
	v_lshl_add_u64 v[220:221], s[24:25], 0, v[170:171]
	s_mov_b32 m0, s22
	ds_read_b128 v[160:163], v211 offset:16384
	ds_read_b128 v[164:167], v211 offset:17408
	ds_read_b128 v[184:187], v211 offset:18432
	ds_read_b128 v[188:191], v211 offset:19456
	ds_read_b128 v[192:195], v211 offset:20480
	ds_read_b128 v[196:199], v211 offset:21504
	ds_read_b128 v[200:203], v211 offset:22528
	ds_read_b128 v[216:219], v211 offset:23552
	global_load_lds_dwordx4 v[220:221], off
	s_add_i32 m0, s22, 0x2000
	s_add_u32 s22, s24, 0xb0000
	v_lshl_add_u64 v[222:223], s[24:25], 0, v[174:175]
	s_addc_u32 s23, s25, 0
	s_add_i32 s48, s42, s28
	global_load_lds_dwordx4 v[222:223], off
	s_mov_b32 m0, s48
	v_lshl_add_u64 v[226:227], s[26:27], 0, v[172:173]
	global_load_lds_dwordx4 v170, s[22:23]
	s_add_i32 m0, s48, 0x2000
	s_nop 0
	global_load_lds_dwordx4 v174, s[22:23]
	v_lshl_add_u64 v[224:225], s[26:27], 0, v[168:169]
	s_mov_b32 m0, s29
	s_nop 0
	global_load_lds_dwordx4 v[224:225], off
	s_mov_b32 m0, s30
	s_nop 0
	global_load_lds_dwordx4 v[226:227], off
	s_waitcnt vmcnt(8)
	s_waitcnt lgkmcnt(0)
	s_barrier
	s_setprio 1
	v_mfma_f32_16x16x32_bf16 v[60:63], v[120:123], v[160:163], v[60:63]
	v_mfma_f32_16x16x32_bf16 v[56:59], v[136:139], v[160:163], v[56:59]
	v_mfma_f32_16x16x32_bf16 v[44:47], v[120:123], v[184:187], v[44:47]
	v_mfma_f32_16x16x32_bf16 v[40:43], v[136:139], v[184:187], v[40:43]
	v_mfma_f32_16x16x32_bf16 v[28:31], v[120:123], v[192:195], v[28:31]
	v_mfma_f32_16x16x32_bf16 v[24:27], v[136:139], v[192:195], v[24:27]
	v_mfma_f32_16x16x32_bf16 v[12:15], v[120:123], v[200:203], v[12:15]
	v_mfma_f32_16x16x32_bf16 v[8:11], v[136:139], v[200:203], v[8:11]
	v_mfma_f32_16x16x32_bf16 v[60:63], v[128:131], v[164:167], v[60:63]
	v_mfma_f32_16x16x32_bf16 v[56:59], v[140:143], v[164:167], v[56:59]
	v_mfma_f32_16x16x32_bf16 v[44:47], v[128:131], v[188:191], v[44:47]
	v_mfma_f32_16x16x32_bf16 v[40:43], v[140:143], v[188:191], v[40:43]
	v_mfma_f32_16x16x32_bf16 v[28:31], v[128:131], v[196:199], v[28:31]
	v_mfma_f32_16x16x32_bf16 v[24:27], v[140:143], v[196:199], v[24:27]
	v_mfma_f32_16x16x32_bf16 v[12:15], v[128:131], v[216:219], v[12:15]
	v_mfma_f32_16x16x32_bf16 v[8:11], v[140:143], v[216:219], v[8:11]
	s_setprio 0
	s_setprio 1
	v_mfma_f32_16x16x32_bf16 v[52:55], v[144:147], v[160:163], v[52:55]
	v_mfma_f32_16x16x32_bf16 v[48:51], v[152:155], v[160:163], v[48:51]
	v_mfma_f32_16x16x32_bf16 v[36:39], v[144:147], v[184:187], v[36:39]
	v_mfma_f32_16x16x32_bf16 v[32:35], v[152:155], v[184:187], v[32:35]
	v_mfma_f32_16x16x32_bf16 v[20:23], v[144:147], v[192:195], v[20:23]
	v_mfma_f32_16x16x32_bf16 v[16:19], v[152:155], v[192:195], v[16:19]
	v_mfma_f32_16x16x32_bf16 v[4:7], v[144:147], v[200:203], v[4:7]
	v_mfma_f32_16x16x32_bf16 v[0:3], v[152:155], v[200:203], v[0:3]
	v_mfma_f32_16x16x32_bf16 v[52:55], v[148:151], v[164:167], v[52:55]
	v_mfma_f32_16x16x32_bf16 v[48:51], v[156:159], v[164:167], v[48:51]
	v_mfma_f32_16x16x32_bf16 v[36:39], v[148:151], v[188:191], v[36:39]
	v_mfma_f32_16x16x32_bf16 v[32:35], v[156:159], v[188:191], v[32:35]
	v_mfma_f32_16x16x32_bf16 v[20:23], v[148:151], v[196:199], v[20:23]
	v_mfma_f32_16x16x32_bf16 v[16:19], v[156:159], v[196:199], v[16:19]
	v_mfma_f32_16x16x32_bf16 v[4:7], v[148:151], v[216:219], v[4:7]
	v_mfma_f32_16x16x32_bf16 v[0:3], v[156:159], v[216:219], v[0:3]
	s_setprio 0
	s_barrier
	s_add_i32 s48, 0, 0x18000
	s_add_i32 s49, 0, 0x1c000
	v_add_u32_e32 v140, s48, v205
	v_add_u32_e32 v156, s49, v205
	ds_read_b128 v[120:123], v140
	ds_read_b128 v[128:131], v140 offset:1024
	ds_read_b128 v[136:139], v140 offset:2048
	ds_read_b128 v[140:143], v140 offset:3072
	ds_read_b128 v[144:147], v156
	ds_read_b128 v[148:151], v156 offset:1024
	ds_read_b128 v[152:155], v156 offset:2048
	ds_read_b128 v[156:159], v156 offset:3072
	s_add_u32 s22, s26, 0xb0000
	s_addc_u32 s23, s27, 0
	s_mov_b32 m0, s31
	ds_read_b128 v[160:163], v211 offset:32768
	ds_read_b128 v[164:167], v211 offset:33792
	ds_read_b128 v[184:187], v211 offset:34816
	ds_read_b128 v[188:191], v211 offset:35840
	ds_read_b128 v[192:195], v211 offset:36864
	ds_read_b128 v[196:199], v211 offset:37888
	ds_read_b128 v[200:203], v211 offset:38912
	ds_read_b128 v[216:219], v211 offset:39936
	global_load_lds_dwordx4 v168, s[22:23]
	s_mov_b32 m0, s33
	s_nop 0
	global_load_lds_dwordx4 v172, s[22:23]
	s_waitcnt vmcnt(8)
	s_waitcnt lgkmcnt(0)
	s_barrier
	s_setprio 1
	v_mfma_f32_16x16x32_bf16 v[132:135], v[120:123], v[160:163], v[132:135]
	v_mfma_f32_16x16x32_bf16 v[124:127], v[136:139], v[160:163], v[124:127]
	v_mfma_f32_16x16x32_bf16 v[108:111], v[120:123], v[184:187], v[108:111]
	v_mfma_f32_16x16x32_bf16 v[104:107], v[136:139], v[184:187], v[104:107]
	v_mfma_f32_16x16x32_bf16 v[92:95], v[120:123], v[192:195], v[92:95]
	v_mfma_f32_16x16x32_bf16 v[88:91], v[136:139], v[192:195], v[88:91]
	v_mfma_f32_16x16x32_bf16 v[76:79], v[120:123], v[200:203], v[76:79]
	v_mfma_f32_16x16x32_bf16 v[72:75], v[136:139], v[200:203], v[72:75]
	v_mfma_f32_16x16x32_bf16 v[132:135], v[128:131], v[164:167], v[132:135]
	v_mfma_f32_16x16x32_bf16 v[124:127], v[140:143], v[164:167], v[124:127]
	v_mfma_f32_16x16x32_bf16 v[108:111], v[128:131], v[188:191], v[108:111]
	v_mfma_f32_16x16x32_bf16 v[104:107], v[140:143], v[188:191], v[104:107]
	v_mfma_f32_16x16x32_bf16 v[92:95], v[128:131], v[196:199], v[92:95]
	v_mfma_f32_16x16x32_bf16 v[88:91], v[140:143], v[196:199], v[88:91]
	v_mfma_f32_16x16x32_bf16 v[76:79], v[128:131], v[216:219], v[76:79]
	v_mfma_f32_16x16x32_bf16 v[72:75], v[140:143], v[216:219], v[72:75]
	s_setprio 0
	s_setprio 1
	v_mfma_f32_16x16x32_bf16 v[116:119], v[144:147], v[160:163], v[116:119]
	v_mfma_f32_16x16x32_bf16 v[112:115], v[152:155], v[160:163], v[112:115]
	v_mfma_f32_16x16x32_bf16 v[100:103], v[144:147], v[184:187], v[100:103]
	v_mfma_f32_16x16x32_bf16 v[96:99], v[152:155], v[184:187], v[96:99]
	v_mfma_f32_16x16x32_bf16 v[84:87], v[144:147], v[192:195], v[84:87]
	v_mfma_f32_16x16x32_bf16 v[80:83], v[152:155], v[192:195], v[80:83]
	v_mfma_f32_16x16x32_bf16 v[68:71], v[144:147], v[200:203], v[68:71]
	v_mfma_f32_16x16x32_bf16 v[64:67], v[152:155], v[200:203], v[64:67]
	v_mfma_f32_16x16x32_bf16 v[116:119], v[148:151], v[164:167], v[116:119]
	v_mfma_f32_16x16x32_bf16 v[112:115], v[156:159], v[164:167], v[112:115]
	v_mfma_f32_16x16x32_bf16 v[100:103], v[148:151], v[188:191], v[100:103]
	v_mfma_f32_16x16x32_bf16 v[96:99], v[156:159], v[188:191], v[96:99]
	v_mfma_f32_16x16x32_bf16 v[84:87], v[148:151], v[196:199], v[84:87]
	v_mfma_f32_16x16x32_bf16 v[80:83], v[156:159], v[196:199], v[80:83]
	v_mfma_f32_16x16x32_bf16 v[68:71], v[148:151], v[216:219], v[68:71]
	v_mfma_f32_16x16x32_bf16 v[64:67], v[156:159], v[216:219], v[64:67]
	s_setprio 0
	s_barrier
	s_add_i32 s22, s48, s28
	v_lshl_add_u64 v[220:221], v[220:221], 0, s[8:9]
	s_mov_b32 m0, s22
	ds_read_b128 v[160:163], v211 offset:49152
	ds_read_b128 v[164:167], v211 offset:50176
	ds_read_b128 v[184:187], v211 offset:51200
	ds_read_b128 v[188:191], v211 offset:52224
	ds_read_b128 v[192:195], v211 offset:53248
	ds_read_b128 v[196:199], v211 offset:54272
	ds_read_b128 v[200:203], v211 offset:55296
	ds_read_b128 v[216:219], v211 offset:56320
	global_load_lds_dwordx4 v[220:221], off
	s_add_i32 m0, s22, 0x2000
	s_add_u32 s22, s24, 0xb0080
	v_lshl_add_u64 v[220:221], v[222:223], 0, s[8:9]
	s_addc_u32 s23, s25, 0
	s_add_i32 s24, s49, s28
	global_load_lds_dwordx4 v[220:221], off
	s_mov_b32 m0, s24
	s_nop 0
	global_load_lds_dwordx4 v170, s[22:23]
	s_add_i32 m0, s24, 0x2000
	s_nop 0
	global_load_lds_dwordx4 v174, s[22:23]
	v_lshl_add_u64 v[220:221], v[224:225], 0, s[8:9]
	s_mov_b32 m0, s37
	s_nop 0
	global_load_lds_dwordx4 v[220:221], off
	v_lshl_add_u64 v[220:221], v[226:227], 0, s[8:9]
	s_mov_b32 m0, s38
	s_nop 0
	global_load_lds_dwordx4 v[220:221], off
	s_waitcnt vmcnt(8)
	s_waitcnt lgkmcnt(0)
	s_barrier
	s_setprio 1
	v_mfma_f32_16x16x32_bf16 v[60:63], v[120:123], v[160:163], v[60:63]
	v_mfma_f32_16x16x32_bf16 v[56:59], v[136:139], v[160:163], v[56:59]
	v_mfma_f32_16x16x32_bf16 v[44:47], v[120:123], v[184:187], v[44:47]
	v_mfma_f32_16x16x32_bf16 v[40:43], v[136:139], v[184:187], v[40:43]
	v_mfma_f32_16x16x32_bf16 v[28:31], v[120:123], v[192:195], v[28:31]
	v_mfma_f32_16x16x32_bf16 v[24:27], v[136:139], v[192:195], v[24:27]
	v_mfma_f32_16x16x32_bf16 v[12:15], v[120:123], v[200:203], v[12:15]
	v_mfma_f32_16x16x32_bf16 v[8:11], v[136:139], v[200:203], v[8:11]
	v_mfma_f32_16x16x32_bf16 v[60:63], v[128:131], v[164:167], v[60:63]
	v_mfma_f32_16x16x32_bf16 v[56:59], v[140:143], v[164:167], v[56:59]
	v_mfma_f32_16x16x32_bf16 v[44:47], v[128:131], v[188:191], v[44:47]
	v_mfma_f32_16x16x32_bf16 v[40:43], v[140:143], v[188:191], v[40:43]
	v_mfma_f32_16x16x32_bf16 v[28:31], v[128:131], v[196:199], v[28:31]
	v_mfma_f32_16x16x32_bf16 v[24:27], v[140:143], v[196:199], v[24:27]
	v_mfma_f32_16x16x32_bf16 v[12:15], v[128:131], v[216:219], v[12:15]
	v_mfma_f32_16x16x32_bf16 v[8:11], v[140:143], v[216:219], v[8:11]
	s_setprio 0
	s_setprio 1
	v_mfma_f32_16x16x32_bf16 v[52:55], v[144:147], v[160:163], v[52:55]
	v_mfma_f32_16x16x32_bf16 v[48:51], v[152:155], v[160:163], v[48:51]
	v_mfma_f32_16x16x32_bf16 v[36:39], v[144:147], v[184:187], v[36:39]
	v_mfma_f32_16x16x32_bf16 v[32:35], v[152:155], v[184:187], v[32:35]
	v_mfma_f32_16x16x32_bf16 v[20:23], v[144:147], v[192:195], v[20:23]
	v_mfma_f32_16x16x32_bf16 v[16:19], v[152:155], v[192:195], v[16:19]
	v_mfma_f32_16x16x32_bf16 v[4:7], v[144:147], v[200:203], v[4:7]
	v_mfma_f32_16x16x32_bf16 v[0:3], v[152:155], v[200:203], v[0:3]
	v_mfma_f32_16x16x32_bf16 v[52:55], v[148:151], v[164:167], v[52:55]
	v_mfma_f32_16x16x32_bf16 v[48:51], v[156:159], v[164:167], v[48:51]
	v_mfma_f32_16x16x32_bf16 v[36:39], v[148:151], v[188:191], v[36:39]
	v_mfma_f32_16x16x32_bf16 v[32:35], v[156:159], v[188:191], v[32:35]
	v_mfma_f32_16x16x32_bf16 v[20:23], v[148:151], v[196:199], v[20:23]
	v_mfma_f32_16x16x32_bf16 v[16:19], v[156:159], v[196:199], v[16:19]
	v_mfma_f32_16x16x32_bf16 v[4:7], v[148:151], v[216:219], v[4:7]
	v_mfma_f32_16x16x32_bf16 v[0:3], v[156:159], v[216:219], v[0:3]
	s_setprio 0
	s_barrier
	s_add_i32 s47, s47, 2
	s_add_u32 s21, s21, 0x100
	s_addc_u32 s46, s46, 0
	s_cmp_gt_u32 s47, 41
	s_mov_b64 s[22:23], s[4:5]
	s_cbranch_scc0 .LBB0_1325
	s_and_b64 vcc, exec, s[10:11]
	s_cbranch_vccz .LBB0_1328
	s_barrier
